# nt cache-policy hint on the once-read f32 input/weight streams of P0 (x, w_in, wp, p) and P3 (w_o, w_up, w_dn, w_g row loads)
# speedup vs baseline: 1.0156x; 1.0156x over previous
; __device__ __forceinline__ void ph_transpose(const TrJob job, LAS unsigned* scr, int gw, int NGW, int lane) {
;     ...
;     for (int item = gw; item < nitems; item += NGW) {
;         const int kb = item / ngrp, gq = item % ngrp, k0 = 64 * kb, r0 = 64 * gq, sb = srcbase_of(job.kind, r0);
;         const int n4 = (lane & 15) * 4; const bool inb = sb + n4 < job.N;
;         f32x4 v[8][2];
; #pragma unroll
;         for (int i = 0; i < 8; ++i) { const int kp = 4 * i + (lane >> 4);
; #pragma unroll
;             for (int q = 0; q < 2; ++q) { const int k = k0 + 2 * kp + q; f32x4 t = {0.f, 0.f, 0.f, 0.f};
;                 if (inb) t = *(const f32x4*)(W + (size_t)(k ^ job.kxor) * job.N + sb + n4);
;                 v[i][q] = t; } }
.LBB0_10:
	s_mul_hi_i32 s1, s44, 0xea0ea0eb
	s_add_i32 s1, s1, s44
	s_lshr_b32 s6, s1, 31
	s_ashr_i32 s45, s1, 7
	s_add_i32 s45, s45, s6
	s_mul_i32 s1, s45, 0xffffdd00
	s_add_i32 s6, s5, s1
	v_add_u32_e32 v3, s6, v89
	v_mov_b32_e32 v4, v2
	v_mov_b32_e32 v5, v2
	s_lshl_b32 s8, s45, 6
	v_cmp_gt_i32_e32 vcc, s36, v3
	s_ashr_i32 s7, s6, 31
	v_mov_b32_e32 v3, v2
	v_mov_b64_e32 v[8:9], v[4:5]
	v_or_b32_e32 v76, s8, v91
	v_lshl_add_u64 v[78:79], s[6:7], 2, v[72:73]
	v_mov_b64_e32 v[6:7], v[2:3]
	s_and_saveexec_b64 s[6:7], vcc
	s_cbranch_execz .LBB0_12
	v_mad_i64_i32 v[6:7], s[22:23], v76, s37, v[78:79]
	global_load_dwordx4 v[6:9], v[6:7], off nt
.LBB0_12:
	s_or_b64 exec, exec, s[6:7]
	v_mov_b64_e32 v[12:13], v[4:5]
	v_or_b32_e32 v82, 1, v76
	v_mov_b64_e32 v[10:11], v[2:3]
	s_and_saveexec_b64 s[6:7], vcc
	s_cbranch_execz .LBB0_14
	v_mad_i64_i32 v[4:5], s[22:23], v82, s37, v[78:79]
	global_load_dwordx4 v[10:13], v[4:5], off nt
.LBB0_14:
	s_or_b64 exec, exec, s[6:7]
	v_mov_b32_e32 v4, v2
	v_mov_b32_e32 v5, v2
	v_mov_b32_e32 v3, v2
	v_mov_b64_e32 v[16:17], v[4:5]
	v_or_b32_e32 v80, 8, v76
	v_mov_b64_e32 v[14:15], v[2:3]
	s_and_saveexec_b64 s[6:7], vcc
	s_cbranch_execz .LBB0_16
	v_mad_i64_i32 v[14:15], s[22:23], v80, s37, v[78:79]
	global_load_dwordx4 v[14:17], v[14:15], off nt
.LBB0_16:
	s_or_b64 exec, exec, s[6:7]
	v_mov_b64_e32 v[20:21], v[4:5]
	v_or_b32_e32 v86, 9, v76
	v_mov_b64_e32 v[18:19], v[2:3]
	s_and_saveexec_b64 s[6:7], vcc
	s_cbranch_execz .LBB0_18
	v_mad_i64_i32 v[4:5], s[22:23], v86, s37, v[78:79]
	global_load_dwordx4 v[18:21], v[4:5], off nt
.LBB0_18:
	s_or_b64 exec, exec, s[6:7]
	v_mov_b32_e32 v4, v2
	v_mov_b32_e32 v5, v2
	v_mov_b32_e32 v3, v2
	v_mov_b64_e32 v[24:25], v[4:5]
	v_or_b32_e32 v84, 16, v76
	v_mov_b64_e32 v[22:23], v[2:3]
	s_and_saveexec_b64 s[6:7], vcc
	s_cbranch_execz .LBB0_20
	v_mad_i64_i32 v[22:23], s[22:23], v84, s37, v[78:79]
	global_load_dwordx4 v[22:25], v[22:23], off nt
.LBB0_20:
	s_or_b64 exec, exec, s[6:7]
	v_mov_b64_e32 v[28:29], v[4:5]
	v_or_b32_e32 v90, 17, v76
	v_mov_b64_e32 v[26:27], v[2:3]
	s_and_saveexec_b64 s[6:7], vcc
	s_cbranch_execz .LBB0_22
	v_mad_i64_i32 v[4:5], s[22:23], v90, s37, v[78:79]
	global_load_dwordx4 v[26:29], v[4:5], off nt
.LBB0_22:
	s_or_b64 exec, exec, s[6:7]
	v_mov_b32_e32 v4, v2
	v_mov_b32_e32 v5, v2
	v_mov_b32_e32 v3, v2
	v_mov_b64_e32 v[32:33], v[4:5]
	v_or_b32_e32 v88, 24, v76
	v_mov_b64_e32 v[30:31], v[2:3]
	s_and_saveexec_b64 s[6:7], vcc
	s_cbranch_execz .LBB0_24
	v_mad_i64_i32 v[30:31], s[22:23], v88, s37, v[78:79]
	global_load_dwordx4 v[30:33], v[30:31], off nt
.LBB0_24:
	s_or_b64 exec, exec, s[6:7]
	v_mov_b64_e32 v[36:37], v[4:5]
	v_or_b32_e32 v94, 25, v76
	v_mov_b64_e32 v[34:35], v[2:3]
	s_and_saveexec_b64 s[6:7], vcc
	s_cbranch_execz .LBB0_26
	v_mad_i64_i32 v[4:5], s[22:23], v94, s37, v[78:79]
	global_load_dwordx4 v[34:37], v[4:5], off nt
.LBB0_26:
	s_or_b64 exec, exec, s[6:7]
	v_mov_b32_e32 v4, v2
	v_mov_b32_e32 v5, v2
	v_mov_b32_e32 v3, v2
	v_mov_b64_e32 v[40:41], v[4:5]
	v_or_b32_e32 v92, 32, v76
	v_mov_b64_e32 v[38:39], v[2:3]
	s_and_saveexec_b64 s[6:7], vcc
	s_cbranch_execz .LBB0_28
	v_mad_i64_i32 v[38:39], s[22:23], v92, s37, v[78:79]
	global_load_dwordx4 v[38:41], v[38:39], off nt
.LBB0_28:
	s_or_b64 exec, exec, s[6:7]
	v_mov_b64_e32 v[44:45], v[4:5]
	v_or_b32_e32 v98, 33, v76
	v_mov_b64_e32 v[42:43], v[2:3]
	s_and_saveexec_b64 s[6:7], vcc
	s_cbranch_execz .LBB0_30
	v_mad_i64_i32 v[4:5], s[22:23], v98, s37, v[78:79]
	global_load_dwordx4 v[42:45], v[4:5], off nt
.LBB0_30:
	s_or_b64 exec, exec, s[6:7]
	v_mov_b32_e32 v4, v2
	v_mov_b32_e32 v5, v2
	v_mov_b32_e32 v3, v2
	v_mov_b64_e32 v[48:49], v[4:5]
	v_or_b32_e32 v96, 40, v76
	v_mov_b64_e32 v[46:47], v[2:3]
	s_and_saveexec_b64 s[6:7], vcc
	s_cbranch_execz .LBB0_32
	v_mad_i64_i32 v[46:47], s[22:23], v96, s37, v[78:79]
	global_load_dwordx4 v[46:49], v[46:47], off nt
.LBB0_32:
	s_or_b64 exec, exec, s[6:7]
	v_mov_b64_e32 v[52:53], v[4:5]
	v_or_b32_e32 v102, 41, v76
	v_mov_b64_e32 v[50:51], v[2:3]
	s_and_saveexec_b64 s[6:7], vcc
	s_cbranch_execz .LBB0_34
	v_mad_i64_i32 v[4:5], s[22:23], v102, s37, v[78:79]
	global_load_dwordx4 v[50:53], v[4:5], off nt
.LBB0_34:
	s_or_b64 exec, exec, s[6:7]
	v_mov_b32_e32 v4, v2
	v_mov_b32_e32 v5, v2
	v_mov_b32_e32 v3, v2
	v_mov_b64_e32 v[56:57], v[4:5]
	v_or_b32_e32 v100, 48, v76
	v_mov_b64_e32 v[54:55], v[2:3]
	s_and_saveexec_b64 s[6:7], vcc
	s_cbranch_execz .LBB0_36
	v_mad_i64_i32 v[54:55], s[22:23], v100, s37, v[78:79]
	global_load_dwordx4 v[54:57], v[54:55], off nt
.LBB0_36:
	s_or_b64 exec, exec, s[6:7]
	v_mov_b64_e32 v[60:61], v[4:5]
	v_or_b32_e32 v104, 49, v76
	v_mov_b64_e32 v[58:59], v[2:3]
	s_and_saveexec_b64 s[6:7], vcc
	s_cbranch_execz .LBB0_38
	v_mad_i64_i32 v[4:5], s[22:23], v104, s37, v[78:79]
	global_load_dwordx4 v[58:61], v[4:5], off nt
.LBB0_38:
	s_or_b64 exec, exec, s[6:7]
	v_mov_b32_e32 v4, v2
	v_mov_b32_e32 v5, v2
	v_mov_b32_e32 v3, v2
	v_mov_b64_e32 v[64:65], v[4:5]
	v_or_b32_e32 v101, 56, v76
	v_mov_b64_e32 v[62:63], v[2:3]
	s_and_saveexec_b64 s[6:7], vcc
	s_cbranch_execz .LBB0_40
	v_mad_i64_i32 v[62:63], s[22:23], v101, s37, v[78:79]
	global_load_dwordx4 v[62:65], v[62:63], off nt
.LBB0_40:
	s_or_b64 exec, exec, s[6:7]
	v_mov_b64_e32 v[68:69], v[4:5]
	v_or_b32_e32 v103, 57, v76
	v_mov_b64_e32 v[66:67], v[2:3]
	s_and_saveexec_b64 s[6:7], vcc
	s_cbranch_execz .LBB0_42
	v_mad_i64_i32 v[4:5], s[22:23], v103, s37, v[78:79]
	global_load_dwordx4 v[66:69], v[4:5], off nt

; __device__ __forceinline__ void ph_transpose(const TrJob job, LAS unsigned* scr, int gw, int NGW, int lane) {
;     ...
;     for (int item = gw; item < nitems; item += NGW) {
;         const int kb = item / ngrp, gq = item % ngrp, k0 = 64 * kb, r0 = 64 * gq, sb = srcbase_of(job.kind, r0);
;         const int n4 = (lane & 15) * 4; const bool inb = sb + n4 < job.N;
;         f32x4 v[8][2];
; #pragma unroll
;         for (int i = 0; i < 8; ++i) { const int kp = 4 * i + (lane >> 4);
; #pragma unroll
;             for (int q = 0; q < 2; ++q) { const int k = k0 + 2 * kp + q; f32x4 t = {0.f, 0.f, 0.f, 0.f};
;                 if (inb) t = *(const f32x4*)(W + (size_t)(k ^ job.kxor) * job.N + sb + n4);
;                 v[i][q] = t; } }
.LBB0_127:
	s_ashr_i32 s6, s15, 31
	s_lshr_b32 s6, s6, 26
	s_add_i32 s6, s15, s6
	s_ashr_i32 s7, s6, 6
	s_lshl_b32 s22, s7, 12
	s_sub_i32 s8, s1, s22
	s_andn2_b32 s6, s6, 63
	v_add_u32_e32 v2, s8, v78
	s_ashr_i32 s9, s8, 31
	v_cmp_gt_i32_e32 vcc, s13, v2
	v_or_b32_e32 v76, s6, v79
	v_lshl_add_u64 v[74:75], s[8:9], 2, v[68:69]
	v_mov_b32_e32 v2, 0
	v_mov_b32_e32 v3, 0
	v_mov_b32_e32 v4, 0
	v_mov_b32_e32 v5, 0
	s_and_saveexec_b64 s[8:9], vcc
	s_cbranch_execz .LBB0_129
	v_ashrrev_i32_e32 v77, 31, v76
	v_lshlrev_b64 v[2:3], 14, v[76:77]
	v_lshl_add_u64 v[2:3], v[74:75], 0, v[2:3]
	global_load_dwordx4 v[2:5], v[2:3], off nt
.LBB0_129:
	s_or_b64 exec, exec, s[8:9]
	v_mov_b32_e32 v6, 0
	v_mov_b32_e32 v10, 0
	v_mov_b32_e32 v11, 0
	v_mov_b32_e32 v12, 0
	v_mov_b32_e32 v13, 0
	s_and_saveexec_b64 s[8:9], vcc
	s_cbranch_execz .LBB0_131
	v_or_b32_e32 v8, 1, v76
	v_ashrrev_i32_e32 v9, 31, v8
	v_lshlrev_b64 v[8:9], 14, v[8:9]
	v_lshl_add_u64 v[8:9], v[74:75], 0, v[8:9]
	global_load_dwordx4 v[10:13], v[8:9], off nt
.LBB0_131:
	s_or_b64 exec, exec, s[8:9]
	v_mov_b32_e32 v7, 0
	v_mov_b32_e32 v8, 0
	v_mov_b32_e32 v9, 0
	s_and_saveexec_b64 s[8:9], vcc
	s_cbranch_execz .LBB0_133
	v_or_b32_e32 v6, 8, v76
	v_ashrrev_i32_e32 v7, 31, v6
	v_lshlrev_b64 v[6:7], 14, v[6:7]
	v_lshl_add_u64 v[6:7], v[74:75], 0, v[6:7]
	global_load_dwordx4 v[6:9], v[6:7], off nt
.LBB0_133:
	s_or_b64 exec, exec, s[8:9]
	v_mov_b32_e32 v14, 0
	v_mov_b32_e32 v18, 0
	v_mov_b32_e32 v19, 0
	v_mov_b32_e32 v20, 0
	v_mov_b32_e32 v21, 0
	s_and_saveexec_b64 s[8:9], vcc
	s_cbranch_execz .LBB0_135
	v_or_b32_e32 v16, 9, v76
	v_ashrrev_i32_e32 v17, 31, v16
	v_lshlrev_b64 v[16:17], 14, v[16:17]
	v_lshl_add_u64 v[16:17], v[74:75], 0, v[16:17]
	global_load_dwordx4 v[18:21], v[16:17], off nt
.LBB0_135:
	s_or_b64 exec, exec, s[8:9]
	v_mov_b32_e32 v15, 0
	v_mov_b32_e32 v16, 0
	v_mov_b32_e32 v17, 0
	s_and_saveexec_b64 s[8:9], vcc
	s_cbranch_execz .LBB0_137
	v_or_b32_e32 v14, 16, v76
	v_ashrrev_i32_e32 v15, 31, v14
	v_lshlrev_b64 v[14:15], 14, v[14:15]
	v_lshl_add_u64 v[14:15], v[74:75], 0, v[14:15]
	global_load_dwordx4 v[14:17], v[14:15], off nt
.LBB0_137:
	s_or_b64 exec, exec, s[8:9]
	v_mov_b32_e32 v22, 0
	v_mov_b32_e32 v26, 0
	v_mov_b32_e32 v27, 0
	v_mov_b32_e32 v28, 0
	v_mov_b32_e32 v29, 0
	s_and_saveexec_b64 s[8:9], vcc
	s_cbranch_execz .LBB0_139
	v_or_b32_e32 v24, 17, v76
	v_ashrrev_i32_e32 v25, 31, v24
	v_lshlrev_b64 v[24:25], 14, v[24:25]
	v_lshl_add_u64 v[24:25], v[74:75], 0, v[24:25]
	global_load_dwordx4 v[26:29], v[24:25], off nt
.LBB0_139:
	s_or_b64 exec, exec, s[8:9]
	v_mov_b32_e32 v23, 0
	v_mov_b32_e32 v24, 0
	v_mov_b32_e32 v25, 0
	s_and_saveexec_b64 s[8:9], vcc
	s_cbranch_execz .LBB0_141
	v_or_b32_e32 v22, 24, v76
	v_ashrrev_i32_e32 v23, 31, v22
	v_lshlrev_b64 v[22:23], 14, v[22:23]
	v_lshl_add_u64 v[22:23], v[74:75], 0, v[22:23]
	global_load_dwordx4 v[22:25], v[22:23], off nt
.LBB0_141:
	s_or_b64 exec, exec, s[8:9]
	v_mov_b32_e32 v30, 0
	v_mov_b32_e32 v34, 0
	v_mov_b32_e32 v35, 0
	v_mov_b32_e32 v36, 0
	v_mov_b32_e32 v37, 0
	s_and_saveexec_b64 s[8:9], vcc
	s_cbranch_execz .LBB0_143
	v_or_b32_e32 v32, 25, v76
	v_ashrrev_i32_e32 v33, 31, v32
	v_lshlrev_b64 v[32:33], 14, v[32:33]
	v_lshl_add_u64 v[32:33], v[74:75], 0, v[32:33]
	global_load_dwordx4 v[34:37], v[32:33], off nt
.LBB0_143:
	s_or_b64 exec, exec, s[8:9]
	v_mov_b32_e32 v31, 0
	v_mov_b32_e32 v32, 0
	v_mov_b32_e32 v33, 0
	s_and_saveexec_b64 s[8:9], vcc
	s_cbranch_execz .LBB0_145
	v_or_b32_e32 v30, 32, v76
	v_ashrrev_i32_e32 v31, 31, v30
	v_lshlrev_b64 v[30:31], 14, v[30:31]
	v_lshl_add_u64 v[30:31], v[74:75], 0, v[30:31]
	global_load_dwordx4 v[30:33], v[30:31], off nt
.LBB0_145:
	s_or_b64 exec, exec, s[8:9]
	v_mov_b32_e32 v38, 0
	v_mov_b32_e32 v42, 0
	v_mov_b32_e32 v43, 0
	v_mov_b32_e32 v44, 0
	v_mov_b32_e32 v45, 0
	s_and_saveexec_b64 s[8:9], vcc
	s_cbranch_execz .LBB0_147
	v_or_b32_e32 v40, 33, v76
	v_ashrrev_i32_e32 v41, 31, v40
	v_lshlrev_b64 v[40:41], 14, v[40:41]
	v_lshl_add_u64 v[40:41], v[74:75], 0, v[40:41]
	global_load_dwordx4 v[42:45], v[40:41], off nt
.LBB0_147:
	s_or_b64 exec, exec, s[8:9]
	v_mov_b32_e32 v39, 0
	v_mov_b32_e32 v40, 0
	v_mov_b32_e32 v41, 0
	s_and_saveexec_b64 s[8:9], vcc
	s_cbranch_execz .LBB0_149
	v_or_b32_e32 v38, 40, v76
	v_ashrrev_i32_e32 v39, 31, v38
	v_lshlrev_b64 v[38:39], 14, v[38:39]
	v_lshl_add_u64 v[38:39], v[74:75], 0, v[38:39]
	global_load_dwordx4 v[38:41], v[38:39], off nt
.LBB0_149:
	s_or_b64 exec, exec, s[8:9]
	v_mov_b32_e32 v46, 0
	v_mov_b32_e32 v50, 0
	v_mov_b32_e32 v51, 0
	v_mov_b32_e32 v52, 0
	v_mov_b32_e32 v53, 0
	s_and_saveexec_b64 s[8:9], vcc
	s_cbranch_execz .LBB0_151
	v_or_b32_e32 v48, 41, v76
	v_ashrrev_i32_e32 v49, 31, v48
	v_lshlrev_b64 v[48:49], 14, v[48:49]
	v_lshl_add_u64 v[48:49], v[74:75], 0, v[48:49]
	global_load_dwordx4 v[50:53], v[48:49], off nt
.LBB0_151:
	s_or_b64 exec, exec, s[8:9]
	v_mov_b32_e32 v47, 0
	v_mov_b32_e32 v48, 0
	v_mov_b32_e32 v49, 0
	s_and_saveexec_b64 s[8:9], vcc
	s_cbranch_execz .LBB0_153
	v_or_b32_e32 v46, 48, v76
	v_ashrrev_i32_e32 v47, 31, v46
	v_lshlrev_b64 v[46:47], 14, v[46:47]
	v_lshl_add_u64 v[46:47], v[74:75], 0, v[46:47]
	global_load_dwordx4 v[46:49], v[46:47], off nt
.LBB0_153:
	s_or_b64 exec, exec, s[8:9]
	v_mov_b32_e32 v54, 0
	v_mov_b32_e32 v60, 0
	v_mov_b32_e32 v61, 0
	v_mov_b32_e32 v62, 0
	v_mov_b32_e32 v63, 0
	s_and_saveexec_b64 s[8:9], vcc
	s_cbranch_execz .LBB0_155
	v_or_b32_e32 v56, 49, v76
	v_ashrrev_i32_e32 v57, 31, v56
	v_lshlrev_b64 v[56:57], 14, v[56:57]
	v_lshl_add_u64 v[56:57], v[74:75], 0, v[56:57]
	global_load_dwordx4 v[60:63], v[56:57], off nt
.LBB0_155:
	s_or_b64 exec, exec, s[8:9]
	v_mov_b32_e32 v55, 0
	v_mov_b32_e32 v56, 0
	v_mov_b32_e32 v57, 0
	s_and_saveexec_b64 s[8:9], vcc
	s_cbranch_execz .LBB0_157
	v_or_b32_e32 v54, 56, v76
	v_ashrrev_i32_e32 v55, 31, v54
	v_lshlrev_b64 v[54:55], 14, v[54:55]
	v_lshl_add_u64 v[54:55], v[74:75], 0, v[54:55]
	global_load_dwordx4 v[54:57], v[54:55], off nt
.LBB0_157:
	s_or_b64 exec, exec, s[8:9]
	v_mov_b32_e32 v58, 0
	v_mov_b32_e32 v64, 0
	v_mov_b32_e32 v65, 0
	v_mov_b32_e32 v66, 0
	v_mov_b32_e32 v67, 0
	s_and_saveexec_b64 s[8:9], vcc
	s_cbranch_execz .LBB0_159
	v_or_b32_e32 v64, 57, v76
	v_ashrrev_i32_e32 v65, 31, v64
	v_lshlrev_b64 v[64:65], 14, v[64:65]
	v_lshl_add_u64 v[64:65], v[74:75], 0, v[64:65]
	global_load_dwordx4 v[64:67], v[64:65], off nt

; __device__ __forceinline__ u32x4 pack8(const f32x4 a, const f32x4 b) { u32x4 w; w.x = cvt_pk_bf16(a[0], a[1]); w.y = cvt_pk_bf16(a[2], a[3]); w.z = cvt_pk_bf16(b[0], b[1]); w.w = cvt_pk_bf16(b[2], b[3]); return w; }
; __device__ __forceinline__ void ph_xprep(const float* __restrict__ x, bf16_t* __restrict__ xb, float* __restrict__ rs0, int gw, int NGW, int lane) {
;     for (int t = gw; t < SEQ; t += NGW) {
;         const f32x4* xr = (const f32x4*)(x + (size_t)t * DM); f32x4 a[8], b[8]; float ss = 0.f;
; #pragma unroll
;         for (int i = 0; i < 8; ++i) { a[i] = xr[(i * 64 + lane) * 2]; b[i] = xr[(i * 64 + lane) * 2 + 1]; }
; #pragma unroll
;         for (int i = 0; i < 8; ++i) { ss += (a[i][0] * a[i][0] + a[i][1] * a[i][1]) + (a[i][2] * a[i][2] + a[i][3] * a[i][3]) + (b[i][0] * b[i][0] + b[i][1] * b[i][1]) + (b[i][2] * b[i][2] + b[i][3] * b[i][3]);
;             *(u32x4*)(xb + (size_t)t * DM + (i * 64 + lane) * 8) = pack8(a[i], b[i]); }
;         ss = wave_sum(ss);
;         if (lane == 0) rs0[t] = rsqrtf(ss * (1.f / DM) + EPS);
.LBB0_178:
	v_add_co_u32_e64 v40, s[6:7], s21, v38
	global_load_dwordx4 v[50:53], v[38:39], off nt
	global_load_dwordx4 v[54:57], v[38:39], off offset:16 nt
	global_load_dwordx4 v[58:61], v[38:39], off offset:2048 nt
	global_load_dwordx4 v[62:65], v[38:39], off offset:2064 nt
	v_addc_co_u32_e64 v41, s[6:7], 0, v39, s[6:7]
	global_load_dwordx4 v[66:69], v[40:41], off offset:-4096 nt
	s_waitcnt lgkmcnt(0)
	v_lshl_add_u64 v[2:3], v[38:39], 0, s[22:23]
	global_load_dwordx4 v[72:75], v[2:3], off offset:16 nt
	v_lshl_add_u64 v[6:7], v[38:39], 0, s[24:25]
	global_load_dwordx4 v[6:9], v[6:7], off offset:16 nt
	v_add_co_u32_e64 v2, s[6:7], s5, v38
	global_load_dwordx4 v[10:13], v[40:41], off nt
	s_nop 0
	v_addc_co_u32_e64 v3, s[6:7], 0, v39, s[6:7]
	global_load_dwordx4 v[2:5], v[2:3], off offset:2048 nt
	v_lshl_add_u64 v[84:85], v[38:39], 0, s[26:27]
	v_add_co_u32_e64 v90, s[6:7], s33, v38
	v_lshl_add_u64 v[86:87], v[38:39], 0, s[28:29]
	v_lshl_add_u64 v[88:89], v[38:39], 0, s[30:31]
	v_addc_co_u32_e64 v91, s[6:7], 0, v39, s[6:7]
	v_lshl_add_u64 v[92:93], v[38:39], 0, s[34:35]
	global_load_dwordx4 v[76:79], v[84:85], off offset:16 nt
	global_load_dwordx4 v[80:83], v[40:41], off offset:2048 nt
	global_load_dwordx4 v[30:33], v[86:87], off offset:16 nt
	global_load_dwordx4 v[22:25], v[88:89], off offset:16 nt
	global_load_dwordx4 v[26:29], v[90:91], off nt
	global_load_dwordx4 v[18:21], v[90:91], off offset:2048 nt
	global_load_dwordx4 v[14:17], v[92:93], off offset:16 nt
	v_lshl_add_u64 v[94:95], s[10:11], 0, v[34:35]
	v_add_co_u32_e64 v88, s[6:7], s38, v94
	s_waitcnt vmcnt(15)
	v_cvt_pk_bf16_f32 v84, v50, v51
	s_nop 0
	v_addc_co_u32_e64 v89, s[6:7], 0, v95, s[6:7]
	v_add_co_u32_e64 v40, s[6:7], s39, v94
	v_mul_f32_e32 v49, v51, v51
	v_mul_f32_e32 v90, v53, v53
	s_waitcnt vmcnt(14)
	v_mul_f32_e32 v91, v55, v55
	v_mul_f32_e32 v92, v57, v57
	v_cvt_pk_bf16_f32 v85, v52, v53
	v_cvt_pk_bf16_f32 v86, v54, v55
	v_cvt_pk_bf16_f32 v87, v56, v57
	s_waitcnt vmcnt(13)
	v_mul_f32_e32 v55, v59, v59
	v_mul_f32_e32 v57, v61, v61
	v_addc_co_u32_e64 v41, s[6:7], 0, v95, s[6:7]
	s_waitcnt vmcnt(12)
	v_mul_f32_e32 v93, v63, v63
	v_fmac_f32_e32 v49, v50, v50
	v_fmac_f32_e32 v90, v52, v52
	v_fmac_f32_e32 v91, v54, v54
	v_fmac_f32_e32 v92, v56, v56
	v_fmac_f32_e32 v55, v58, v58
	v_fmac_f32_e32 v57, v60, v60
	s_waitcnt vmcnt(11)
	v_mul_f32_e32 v54, v67, v67
	v_mul_f32_e32 v56, v69, v69
	v_mul_f32_e32 v94, v65, v65
	global_store_dwordx4 v[40:41], v[84:87], off offset:-4096
	v_fmac_f32_e32 v93, v62, v62
	v_cvt_pk_bf16_f32 v50, v58, v59
	v_cvt_pk_bf16_f32 v51, v60, v61
	s_waitcnt vmcnt(11)
	v_mul_f32_e32 v58, v73, v73
	v_add_f32_e32 v49, v49, v90
	v_add_f32_e32 v55, v55, v57
	v_fmac_f32_e32 v54, v66, v66
	v_fmac_f32_e32 v56, v68, v68
	v_fmac_f32_e32 v94, v64, v64
	v_cvt_pk_bf16_f32 v52, v62, v63
	v_cvt_pk_bf16_f32 v53, v64, v65
	v_mul_f32_e32 v59, v75, v75
	global_store_dwordx4 v[88:89], v[50:53], off offset:1024
	v_fmac_f32_e32 v58, v72, v72
	v_add_f32_e32 v49, v49, v91
	v_add_f32_e32 v50, v55, v93
	v_add_f32_e32 v51, v54, v56
	v_fmac_f32_e32 v59, v74, v74
	v_add_f32_e32 v49, v92, v49
	v_add_f32_e32 v50, v94, v50
	v_add_f32_e32 v51, v51, v58
	v_add_f32_e32 v49, v49, v50
	v_add_f32_e32 v50, v59, v51
	v_add_f32_e32 v49, v49, v50
	v_cvt_pk_bf16_f32 v50, v66, v67
	v_cvt_pk_bf16_f32 v51, v68, v69
	v_cvt_pk_bf16_f32 v52, v72, v73
	v_cvt_pk_bf16_f32 v53, v74, v75
	global_store_dwordx4 v[88:89], v[50:53], off offset:2048
	v_cmp_lt_i32_e64 s[6:7], v42, v36
	s_waitcnt vmcnt(10)
	v_mul_f32_e32 v50, v3, v3
	v_mul_f32_e32 v51, v5, v5
	v_fmac_f32_e32 v50, v2, v2
	v_fmac_f32_e32 v51, v4, v4
	v_add_f32_e32 v50, v50, v51
	v_mul_f32_e32 v51, v7, v7
	v_fmac_f32_e32 v51, v6, v6
	v_add_f32_e32 v50, v50, v51
	v_mul_f32_e32 v51, v9, v9
	v_fmac_f32_e32 v51, v8, v8
	v_add_f32_e32 v50, v51, v50
	v_add_f32_e32 v49, v49, v50
	v_cvt_pk_bf16_f32 v2, v2, v3
	v_mul_f32_e32 v3, v11, v11
	v_mul_f32_e32 v50, v13, v13
	v_fmac_f32_e32 v3, v10, v10
	v_fmac_f32_e32 v50, v12, v12
	v_add_f32_e32 v3, v3, v50
	s_waitcnt vmcnt(9)
; __device__ __forceinline__ u32x4 pack8(const f32x4 a, const f32x4 b) { u32x4 w; w.x = cvt_pk_bf16(a[0], a[1]); w.y = cvt_pk_bf16(a[2], a[3]); w.z = cvt_pk_bf16(b[0], b[1]); w.w = cvt_pk_bf16(b[2], b[3]); return w; }
; __device__ __forceinline__ float wave_sum(float v) {
; #pragma unroll
;     for (int o = 1; o < 64; o <<= 1) v += __shfl_xor(v, o);
;     return v;
; __device__ __forceinline__ void ph_xprep(const float* __restrict__ x, bf16_t* __restrict__ xb, float* __restrict__ rs0, int gw, int NGW, int lane) {
;     ...
;         for (int i = 0; i < 8; ++i) { ss += (a[i][0] * a[i][0] + a[i][1] * a[i][1]) + (a[i][2] * a[i][2] + a[i][3] * a[i][3]) + (b[i][0] * b[i][0] + b[i][1] * b[i][1]) + (b[i][2] * b[i][2] + b[i][3] * b[i][3]);
;             *(u32x4*)(xb + (size_t)t * DM + (i * 64 + lane) * 8) = pack8(a[i], b[i]); }
;         ss = wave_sum(ss);
;         if (lane == 0) rs0[t] = rsqrtf(ss * (1.f / DM) + EPS);
	v_mul_f32_e32 v50, v77, v77
	v_fmac_f32_e32 v50, v76, v76
	v_add_f32_e32 v3, v3, v50
	v_mul_f32_e32 v50, v79, v79
	v_fmac_f32_e32 v50, v78, v78
	v_add_f32_e32 v3, v50, v3
	v_add_f32_e32 v3, v49, v3
	s_waitcnt vmcnt(8)
	v_mul_f32_e32 v49, v81, v81
	v_mul_f32_e32 v50, v83, v83
	v_fmac_f32_e32 v49, v80, v80
	v_fmac_f32_e32 v50, v82, v82
	v_add_f32_e32 v49, v49, v50
	s_waitcnt vmcnt(7)
	v_mul_f32_e32 v50, v31, v31
	v_fmac_f32_e32 v50, v30, v30
	v_add_f32_e32 v49, v49, v50
	v_mul_f32_e32 v50, v33, v33
	v_fmac_f32_e32 v50, v32, v32
	v_add_f32_e32 v49, v50, v49
	v_add_f32_e32 v3, v3, v49
	s_waitcnt vmcnt(5)
	v_mul_f32_e32 v49, v27, v27
	v_mul_f32_e32 v50, v29, v29
	v_fmac_f32_e32 v49, v26, v26
	v_fmac_f32_e32 v50, v28, v28
	v_add_f32_e32 v49, v49, v50
	v_mul_f32_e32 v50, v23, v23
	v_fmac_f32_e32 v50, v22, v22
	v_add_f32_e32 v49, v49, v50
	v_mul_f32_e32 v50, v25, v25
	v_fmac_f32_e32 v50, v24, v24
	v_add_f32_e32 v49, v50, v49
	v_add_f32_e32 v3, v3, v49
	s_waitcnt vmcnt(4)
	v_mul_f32_e32 v49, v19, v19
	v_mul_f32_e32 v50, v21, v21
	v_fmac_f32_e32 v49, v18, v18
	v_fmac_f32_e32 v50, v20, v20
	v_add_f32_e32 v49, v49, v50
	s_waitcnt vmcnt(3)
	v_mul_f32_e32 v50, v15, v15
	v_fmac_f32_e32 v50, v14, v14
	v_add_f32_e32 v49, v49, v50
	v_mul_f32_e32 v50, v17, v17
	v_fmac_f32_e32 v50, v16, v16
	v_add_f32_e32 v49, v50, v49
	v_add_f32_e32 v49, v3, v49
	v_cndmask_b32_e64 v3, v1, v42, s[6:7]
	v_lshlrev_b32_e32 v3, 2, v3
	ds_bpermute_b32 v50, v3, v49
	v_cmp_lt_i32_e64 s[6:7], v43, v36
	v_cvt_pk_bf16_f32 v3, v4, v5
	v_cvt_pk_bf16_f32 v4, v6, v7
	v_cvt_pk_bf16_f32 v5, v8, v9
	global_store_dwordx4 v[88:89], v[2:5], off offset:3072
	s_waitcnt lgkmcnt(0)
	v_add_f32_e32 v6, v49, v50
	v_cndmask_b32_e64 v2, v1, v43, s[6:7]
	v_lshlrev_b32_e32 v2, 2, v2
	ds_bpermute_b32 v7, v2, v6
	v_cmp_lt_i32_e64 s[6:7], v44, v36
	v_cvt_pk_bf16_f32 v2, v10, v11
	v_cvt_pk_bf16_f32 v3, v12, v13
	v_cvt_pk_bf16_f32 v4, v76, v77
	s_waitcnt lgkmcnt(0)
	v_add_f32_e32 v6, v6, v7
	v_cvt_pk_bf16_f32 v5, v78, v79
	v_cndmask_b32_e64 v7, v1, v44, s[6:7]
	v_lshlrev_b32_e32 v7, 2, v7
	ds_bpermute_b32 v7, v7, v6
	v_cmp_lt_i32_e64 s[6:7], v45, v36
	global_store_dwordx4 v[40:41], v[2:5], off
	s_waitcnt lgkmcnt(0)
	v_add_f32_e32 v6, v6, v7
	v_cndmask_b32_e64 v5, v1, v45, s[6:7]
	v_lshlrev_b32_e32 v5, 2, v5
	ds_bpermute_b32 v7, v5, v6
	v_cvt_pk_bf16_f32 v2, v80, v81
	v_cvt_pk_bf16_f32 v3, v82, v83
	v_cvt_pk_bf16_f32 v4, v30, v31
	v_cmp_lt_i32_e64 s[6:7], v46, v36
	v_cvt_pk_bf16_f32 v5, v32, v33
	global_store_dwordx4 v[40:41], v[2:5], off offset:1024
	s_waitcnt lgkmcnt(0)
	v_add_f32_e32 v6, v6, v7
	v_cndmask_b32_e64 v4, v1, v46, s[6:7]
	v_lshlrev_b32_e32 v4, 2, v4
	ds_bpermute_b32 v7, v4, v6
	v_cvt_pk_bf16_f32 v2, v26, v27
	v_cvt_pk_bf16_f32 v3, v28, v29
	v_cmp_lt_i32_e64 s[6:7], v47, v36
	v_cvt_pk_bf16_f32 v4, v22, v23
	v_cvt_pk_bf16_f32 v5, v24, v25
	global_store_dwordx4 v[40:41], v[2:5], off offset:2048
	s_nop 1
	v_cndmask_b32_e64 v3, v1, v47, s[6:7]
	s_waitcnt lgkmcnt(0)
	v_add_f32_e32 v2, v6, v7
	v_lshlrev_b32_e32 v3, 2, v3
	ds_bpermute_b32 v3, v3, v2
	v_cvt_pk_bf16_f32 v4, v18, v19
	v_cvt_pk_bf16_f32 v5, v20, v21
	v_cvt_pk_bf16_f32 v6, v14, v15
	v_cvt_pk_bf16_f32 v7, v16, v17
	global_store_dwordx4 v[40:41], v[4:7], off offset:3072
	s_and_saveexec_b64 s[36:37], vcc
	s_cbranch_execz .LBB0_177
	s_waitcnt lgkmcnt(0)
	v_add_f32_e32 v2, v2, v3
	v_fmamk_f32 v2, v2, 0x39800000, v48
	v_mul_f32_e32 v3, 0x4b800000, v2
	v_cmp_gt_f32_e64 s[6:7], s40, v2
	s_add_u32 s42, s10, s1
	s_addc_u32 s43, s11, s4
	v_cndmask_b32_e64 v2, v2, v3, s[6:7]
	v_rsq_f32_e32 v2, v2
	s_nop 0
	v_mul_f32_e32 v3, 0x45800000, v2
	v_cndmask_b32_e64 v2, v2, v3, s[6:7]
	global_store_dword v37, v2, s[42:43]
	s_branch .LBB0_177

; __device__ __forceinline__ u32x4 pack8(const f32x4 a, const f32x4 b) { u32x4 w; w.x = cvt_pk_bf16(a[0], a[1]); w.y = cvt_pk_bf16(a[2], a[3]); w.z = cvt_pk_bf16(b[0], b[1]); w.w = cvt_pk_bf16(b[2], b[3]); return w; }
; __device__ __forceinline__ void ph_pprep(const float* __restrict__ p, bf16_t* __restrict__ pb, size_t gt, size_t NGT) {
;     const size_t n8 = (size_t)SEQ * PLE / 8;
;     for (size_t i = gt; i < n8; i += NGT) {
;         const f32x4 a = ((const f32x4*)p)[2 * i], b = ((const f32x4*)p)[2 * i + 1]; ((u32x4*)pb)[i] = pack8(a, b); }
; }
; __device__ __forceinline__ void ph_trig(const int* __restrict__ positions, float* __restrict__ cosT, float* __restrict__ sinT, size_t gt, size_t NGT) {
;   for (size_t ii = gt; ii < (size_t)SEQ * 32; ii += NGT) { const int i = (int)ii;
;     const int t = i >> 5, f = i & 31;
;     const float invf = powf(10000.f, -(float)f / 32.f);
;     const float ang = (float)positions[t] * invf;
;     float s, c; sincosf(ang, &s, &c); cosT[i] = c; sinT[i] = s; }
.LBB0_184:
	global_load_dwordx4 v[10:13], v[6:7], off offset:-16 nt
	global_load_dwordx4 v[14:17], v[6:7], off nt
	v_lshl_add_u64 v[8:9], v[8:9], 0, s[14:15]
	v_cmp_lt_u64_e32 vcc, s[22:23], v[8:9]
	v_lshl_add_u64 v[6:7], v[6:7], 0, s[20:21]
	s_or_b64 s[8:9], vcc, s[8:9]
	s_waitcnt vmcnt(1)
	v_cvt_pk_bf16_f32 v10, v10, v11
	v_cvt_pk_bf16_f32 v11, v12, v13
	s_waitcnt vmcnt(0)
	v_cvt_pk_bf16_f32 v12, v14, v15
	v_cvt_pk_bf16_f32 v13, v16, v17
	global_store_dwordx4 v[4:5], v[10:13], off
	v_lshl_add_u64 v[4:5], v[4:5], 0, s[6:7]
	s_andn2_b64 exec, exec, s[8:9]
	s_cbranch_execnz .LBB0_184
	s_or_b64 exec, exec, s[8:9]
	v_and_b32_e32 v1, 31, v70
	v_cvt_f32_ubyte0_e32 v1, v1
	v_mul_f32_e32 v1, 0xbd000000, v1
	v_mov_b32_e32 v4, 0x461c4000
	v_cmp_eq_f32_e32 vcc, 0, v1
	s_mov_b32 s1, 0x3f2aaaab
	s_mov_b32 s5, 0x42b17218
	v_cndmask_b32_e64 v14, v4, 1.0, vcc
	v_frexp_mant_f32_e32 v4, v14
	v_cmp_gt_f32_e64 s[6:7], s1, v4
	s_mov_b32 s1, 0x3f317218
	s_mov_b32 s4, 0x7f800000
	v_cndmask_b32_e64 v5, 1.0, 2.0, s[6:7]
	v_mul_f32_e32 v4, v4, v5
	v_add_f32_e32 v7, 1.0, v4
	v_rcp_f32_e32 v12, v7
	v_add_f32_e32 v5, -1.0, v7
	v_sub_f32_e32 v9, v4, v5
	v_add_f32_e32 v5, -1.0, v4
	v_mul_f32_e32 v13, v5, v12
	v_mul_f32_e32 v6, v7, v13
	v_fma_f32 v8, v13, v7, -v6
	v_fmac_f32_e32 v8, v13, v9
	v_add_f32_e32 v4, v6, v8
	v_sub_f32_e32 v7, v5, v4
	v_pk_add_f32 v[10:11], v[4:5], v[6:7] neg_lo:[0,1] neg_hi:[0,1]
	v_mov_b32_e32 v9, v4
	v_pk_add_f32 v[4:5], v[10:11], v[8:9] neg_lo:[0,1] neg_hi:[0,1]
	v_mov_b32_e32 v8, 0x3e91f4c4
	v_add_f32_e32 v4, v4, v5
	v_add_f32_e32 v4, v7, v4
	v_mul_f32_e32 v5, v12, v4
	v_add_f32_e32 v4, v13, v5
	v_sub_f32_e32 v6, v4, v13
	v_sub_f32_e32 v15, v5, v6
	v_mul_f32_e32 v5, v4, v4
	v_fma_f32 v7, v4, v4, -v5
	v_add_f32_e32 v6, v15, v15
	v_fmac_f32_e32 v7, v4, v6
	v_add_f32_e32 v6, v5, v7
	v_fmac_f32_e32 v8, 0x3e76c4e1, v6
	v_fmaak_f32 v8, v6, v8, 0x3ecccdef
	v_sub_f32_e32 v5, v6, v5
	v_sub_f32_e32 v16, v7, v5
	v_mul_f32_e32 v5, v6, v8
	v_fma_f32 v7, v6, v8, -v5
	v_fmac_f32_e32 v7, v16, v8
	v_add_f32_e32 v8, v5, v7
	v_add_f32_e32 v9, 0x3f2aaaaa, v8
	v_sub_f32_e32 v5, v8, v5
	v_sub_f32_e32 v5, v7, v5
	v_add_f32_e32 v7, 0xbf2aaaaa, v9
	v_add_f32_e32 v5, 0x31739010, v5
	v_sub_f32_e32 v7, v8, v7
	v_pk_mul_f32 v[10:11], v[4:5], v[6:7]
	v_pk_add_f32 v[12:13], v[4:5], v[6:7]
	v_fma_f32 v8, v6, v4, -v10
	v_fmac_f32_e32 v8, v6, v15
	v_mov_b32_e32 v11, v13
	v_fmac_f32_e32 v8, v16, v4
	v_pk_add_f32 v[6:7], v[10:11], v[8:9]
	v_ldexp_f32 v16, v15, 1
	v_sub_f32_e32 v5, v6, v10
	v_sub_f32_e32 v5, v8, v5
	v_sub_f32_e32 v8, v9, v7
	v_add_f32_e32 v11, v13, v8
	v_pk_mul_f32 v[8:9], v[6:7], v[6:7] op_sel:[0,1] op_sel_hi:[1,0]
	v_cvt_f64_f32_e32 v[12:13], v14
	v_frexp_exp_i32_f64_e32 v9, v[12:13]
	v_subbrev_co_u32_e64 v9, s[6:7], 0, v9, s[6:7]
	v_cvt_f32_i32_e32 v9, v9
	v_fma_f32 v10, v6, v7, -v8
	v_fmac_f32_e32 v10, v6, v11
	v_fmac_f32_e32 v10, v5, v7
	v_mul_f32_e32 v6, 0x3f317218, v9
	v_fma_f32 v5, v9, s1, -v6
	v_fmamk_f32 v12, v9, 0xb102e308, v5
	v_ldexp_f32 v13, v4, 1
	v_add_f32_e32 v7, v8, v10
	v_pk_add_f32 v[4:5], v[6:7], v[12:13]
	v_mov_b32_e32 v14, v7
	v_mov_b32_e32 v15, v5
	v_mov_b32_e32 v9, v13
	v_pk_add_f32 v[8:9], v[14:15], v[8:9] neg_lo:[0,1] neg_hi:[0,1]
	v_mov_b32_e32 v11, v7
	v_pk_add_f32 v[8:9], v[10:11], v[8:9] neg_lo:[0,1] neg_hi:[0,1]
	v_mov_b32_e32 v13, v4
	v_add_f32_e32 v7, v16, v8
	v_add_f32_e32 v7, v7, v9
	v_pk_add_f32 v[8:9], v[4:5], v[6:7] neg_lo:[0,1] neg_hi:[0,1]
	v_pk_add_f32 v[10:11], v[4:5], v[6:7]
	v_mov_b32_e32 v6, v7
	v_mov_b32_e32 v9, v11
	v_pk_add_f32 v[14:15], v[12:13], v[8:9] neg_lo:[0,1] neg_hi:[0,1]
	v_pk_add_f32 v[8:9], v[12:13], v[8:9]
	v_mov_b32_e32 v7, v4
	v_pk_add_f32 v[12:13], v[8:9], v[4:5] op_sel:[1,0] op_sel_hi:[0,1] neg_lo:[0,1] neg_hi:[0,1]
	v_pk_add_f32 v[16:17], v[10:11], v[12:13] op_sel_hi:[1,0] neg_lo:[0,1] neg_hi:[0,1]
	v_mov_b32_e32 v10, v11
	v_mov_b32_e32 v11, v9
	v_pk_mov_b32 v[12:13], v[4:5], v[12:13] op_sel:[1,0]
	v_mov_b32_e32 v16, v14
	v_pk_add_f32 v[10:11], v[10:11], v[12:13] neg_lo:[0,1] neg_hi:[0,1]
	v_mov_b32_e32 v15, v9
	v_pk_add_f32 v[4:5], v[6:7], v[10:11] neg_lo:[0,1] neg_hi:[0,1]
	s_movk_i32 s1, 0x204
	v_pk_add_f32 v[6:7], v[16:17], v[4:5]
	s_load_dwordx2 s[18:19], s[18:19], 0x10
	v_pk_add_f32 v[10:11], v[6:7], v[6:7] op_sel:[0,1] op_sel_hi:[1,0]
	s_mov_b64 s[20:21], 0
	v_pk_add_f32 v[8:9], v[8:9], v[10:11] op_sel:[1,0] op_sel_hi:[0,1]
	v_mov_b32_e32 v7, v8
	v_pk_add_f32 v[12:13], v[6:7], v[14:15] neg_lo:[0,1] neg_hi:[0,1]
	v_mov_b32_e32 v5, v10
	v_sub_f32_e32 v6, v6, v12
	v_pk_add_f32 v[4:5], v[4:5], v[12:13] neg_lo:[0,1] neg_hi:[0,1]
	v_sub_f32_e32 v6, v14, v6
	v_add_f32_e32 v4, v4, v6
	v_add_f32_e32 v4, v4, v5
	v_add_f32_e32 v5, v8, v4
	v_sub_f32_e32 v6, v5, v8
	v_sub_f32_e32 v4, v4, v6
	v_mul_f32_e32 v6, v1, v5
	v_fma_f32 v5, v1, v5, -v6
	v_fmac_f32_e32 v5, v1, v4
	v_add_f32_e32 v4, v6, v5
	v_cmp_class_f32_e64 s[6:7], v6, s1
	v_sub_f32_e32 v7, v4, v6
	v_sub_f32_e32 v5, v5, v7
	v_cndmask_b32_e64 v4, v4, v6, s[6:7]
	v_mov_b32_e32 v6, 0x37000000
	v_cmp_eq_f32_e64 s[6:7], s5, v4
	s_mov_b32 s28, 0xf534ddc0
	s_mov_b32 s29, 0xfc2757d1
	v_cndmask_b32_e64 v6, 0, v6, s[6:7]
	v_sub_f32_e32 v7, v4, v6
	s_mov_b32 s6, 0x3fb8aa3b
	v_mul_f32_e32 v8, 0x3fb8aa3b, v7
	v_fma_f32 v9, v7, s6, -v8
	v_rndne_f32_e32 v10, v8
	v_fmamk_f32 v9, v7, 0x32a5705f, v9
	v_sub_f32_e32 v8, v8, v10
	v_add_f32_e32 v8, v8, v9
	v_exp_f32_e32 v8, v8
	v_cvt_i32_f32_e32 v9, v10
	v_cmp_neq_f32_e64 s[6:7], |v4|, s4
	s_mov_b32 s4, 0xc2ce8ed0
	s_mov_b32 s30, 0x4e441529
	v_cndmask_b32_e64 v4, 0, v5, s[6:7]
	v_ldexp_f32 v5, v8, v9
	v_cmp_ngt_f32_e64 s[6:7], s4, v7
	v_add_f32_e32 v4, v6, v4
	v_mov_b32_e32 v6, 0x7f800000
	v_cndmask_b32_e64 v5, 0, v5, s[6:7]
	v_cmp_nlt_f32_e64 s[6:7], s5, v7
	v_cmp_neq_f32_e64 s[4:5], v1, |v1|
	v_mov_b32_e32 v7, 0
	v_cndmask_b32_e64 v5, v6, v5, s[6:7]
	v_fma_f32 v4, v5, v4, v5
	v_cmp_class_f32_e64 s[6:7], v5, s1
	s_mov_b32 s31, 0xa2f9836e
	s_mov_b32 s33, 0x3fc90fda
	v_cndmask_b32_e64 v4, v4, v5, s[6:7]
	v_cndmask_b32_e64 v5, v6, 0, s[4:5]
	v_cndmask_b32_e64 v5, v5, 1.0, vcc
	v_cmp_class_f32_e64 s[4:5], v1, s1
	s_brev_b32 s1, 18
	s_mov_b32 s34, 0x3f22f983
	v_cndmask_b32_e64 v1, |v4|, v5, s[4:5]
	s_lshl_b64 s[4:5], s[2:3], 11
	s_add_u32 s4, s10, s4
	s_addc_u32 s5, s11, s5
	v_lshl_add_u64 v[4:5], v[70:71], 2, s[4:5]
	s_mov_b64 s[4:5], 0x200000
	v_lshl_add_u64 v[4:5], v[4:5], 0, s[4:5]
	s_lshl_b64 s[22:23], s[74:75], 11
	s_mov_b32 s3, 0xfe5163ab
	s_mov_b32 s4, 0x3c439041
	s_mov_b32 s5, 0xdb629599
	s_mov_b32 s35, 0xbfc90fda
	v_mov_b32_e32 v8, 0x3c0881c4
	v_mov_b32_e32 v9, 0xbab64f3b
	s_brev_b32 s36, 1
	s_movk_i32 s37, 0x1f8
	s_mov_b64 s[24:25], 0x7ffff
	v_not_b32_e32 v10, 63
	v_not_b32_e32 v11, 31
	v_mov_b32_e32 v12, 0x7fc00000
	s_branch .LBB0_187

; __device__ __forceinline__ void ph_transpose(const TrJob job, LAS unsigned* scr, int gw, int NGW, int lane) {
;     ...
;     for (int item = gw; item < nitems; item += NGW) {
;         const int kb = item / ngrp, gq = item % ngrp, k0 = 64 * kb, r0 = 64 * gq, sb = srcbase_of(job.kind, r0);
;         const int n4 = (lane & 15) * 4; const bool inb = sb + n4 < job.N;
;         f32x4 v[8][2];
; #pragma unroll
;         for (int i = 0; i < 8; ++i) { const int kp = 4 * i + (lane >> 4);
; #pragma unroll
;             for (int q = 0; q < 2; ++q) { const int k = k0 + 2 * kp + q; f32x4 t = {0.f, 0.f, 0.f, 0.f};
;                 if (inb) t = *(const f32x4*)(W + (size_t)(k ^ job.kxor) * job.N + sb + n4);
;                 v[i][q] = t; } }
.LBB0_757:
	s_ashr_i32 s1, s27, 31
	s_lshr_b32 s1, s1, 26
	s_add_i32 s1, s27, s1
	s_ashr_i32 s11, s1, 6
	s_and_b32 s10, s1, 0xffffffc0
	s_lshl_b32 s1, s11, 12
	s_sub_i32 s12, s5, s1
	v_add_u32_e32 v3, s12, v71
	v_mov_b32_e32 v4, v2
	v_mov_b32_e32 v5, v2
	v_cmp_gt_i32_e32 vcc, s4, v3
	s_ashr_i32 s13, s12, 31
	v_mov_b32_e32 v3, v2
	v_mov_b64_e32 v[8:9], v[4:5]
	v_or_b32_e32 v76, s10, v85
	v_lshl_add_u64 v[78:79], s[12:13], 2, v[72:73]
	v_mov_b64_e32 v[6:7], v[2:3]
	s_and_saveexec_b64 s[12:13], vcc
	s_cbranch_execz .LBB0_759
	v_xor_b32_e32 v6, 0x800, v76
	v_ashrrev_i32_e32 v7, 31, v6
	v_lshlrev_b64 v[6:7], 14, v[6:7]
	v_lshl_add_u64 v[6:7], v[78:79], 0, v[6:7]
	global_load_dwordx4 v[6:9], v[6:7], off nt
.LBB0_759:
	s_or_b64 exec, exec, s[12:13]
	v_mov_b64_e32 v[12:13], v[4:5]
	v_mov_b64_e32 v[10:11], v[2:3]
	s_and_saveexec_b64 s[12:13], vcc
	s_cbranch_execz .LBB0_761
	v_xor_b32_e32 v4, 0x801, v76
	v_ashrrev_i32_e32 v5, 31, v4
	v_lshlrev_b64 v[4:5], 14, v[4:5]
	v_lshl_add_u64 v[4:5], v[78:79], 0, v[4:5]
	global_load_dwordx4 v[10:13], v[4:5], off nt
.LBB0_761:
	s_or_b64 exec, exec, s[12:13]
	v_mov_b32_e32 v4, v2
	v_mov_b32_e32 v5, v2
	v_mov_b32_e32 v3, v2
	v_mov_b64_e32 v[16:17], v[4:5]
	v_mov_b64_e32 v[14:15], v[2:3]
	s_and_saveexec_b64 s[12:13], vcc
	s_cbranch_execz .LBB0_763
	v_xor_b32_e32 v14, 0x808, v76
	v_ashrrev_i32_e32 v15, 31, v14
	v_lshlrev_b64 v[14:15], 14, v[14:15]
	v_lshl_add_u64 v[14:15], v[78:79], 0, v[14:15]
	global_load_dwordx4 v[14:17], v[14:15], off nt
.LBB0_763:
	s_or_b64 exec, exec, s[12:13]
	v_mov_b64_e32 v[20:21], v[4:5]
	v_mov_b64_e32 v[18:19], v[2:3]
	s_and_saveexec_b64 s[12:13], vcc
	s_cbranch_execz .LBB0_765
	v_xor_b32_e32 v4, 0x809, v76
	v_ashrrev_i32_e32 v5, 31, v4
	v_lshlrev_b64 v[4:5], 14, v[4:5]
	v_lshl_add_u64 v[4:5], v[78:79], 0, v[4:5]
	global_load_dwordx4 v[18:21], v[4:5], off nt
.LBB0_765:
	s_or_b64 exec, exec, s[12:13]
	v_mov_b32_e32 v4, v2
	v_mov_b32_e32 v5, v2
	v_mov_b32_e32 v3, v2
	v_mov_b64_e32 v[24:25], v[4:5]
	v_mov_b64_e32 v[22:23], v[2:3]
	s_and_saveexec_b64 s[12:13], vcc
	s_cbranch_execz .LBB0_767
	v_xor_b32_e32 v22, 0x810, v76
	v_ashrrev_i32_e32 v23, 31, v22
	v_lshlrev_b64 v[22:23], 14, v[22:23]
	v_lshl_add_u64 v[22:23], v[78:79], 0, v[22:23]
	global_load_dwordx4 v[22:25], v[22:23], off nt
.LBB0_767:
	s_or_b64 exec, exec, s[12:13]
	v_mov_b64_e32 v[28:29], v[4:5]
	v_mov_b64_e32 v[26:27], v[2:3]
	s_and_saveexec_b64 s[12:13], vcc
	s_cbranch_execz .LBB0_769
	v_xor_b32_e32 v4, 0x811, v76
	v_ashrrev_i32_e32 v5, 31, v4
	v_lshlrev_b64 v[4:5], 14, v[4:5]
	v_lshl_add_u64 v[4:5], v[78:79], 0, v[4:5]
	global_load_dwordx4 v[26:29], v[4:5], off nt
.LBB0_769:
	s_or_b64 exec, exec, s[12:13]
	v_mov_b32_e32 v4, v2
	v_mov_b32_e32 v5, v2
	v_mov_b32_e32 v3, v2
	v_mov_b64_e32 v[32:33], v[4:5]
	v_mov_b64_e32 v[30:31], v[2:3]
	s_and_saveexec_b64 s[12:13], vcc
	s_cbranch_execz .LBB0_771
	v_xor_b32_e32 v30, 0x818, v76
	v_ashrrev_i32_e32 v31, 31, v30
	v_lshlrev_b64 v[30:31], 14, v[30:31]
	v_lshl_add_u64 v[30:31], v[78:79], 0, v[30:31]
	global_load_dwordx4 v[30:33], v[30:31], off nt
.LBB0_771:
	s_or_b64 exec, exec, s[12:13]
	v_mov_b64_e32 v[36:37], v[4:5]
	v_mov_b64_e32 v[34:35], v[2:3]
	s_and_saveexec_b64 s[12:13], vcc
	s_cbranch_execz .LBB0_773
	v_xor_b32_e32 v4, 0x819, v76
	v_ashrrev_i32_e32 v5, 31, v4
	v_lshlrev_b64 v[4:5], 14, v[4:5]
	v_lshl_add_u64 v[4:5], v[78:79], 0, v[4:5]
	global_load_dwordx4 v[34:37], v[4:5], off nt
.LBB0_773:
	s_or_b64 exec, exec, s[12:13]
	v_mov_b32_e32 v4, v2
	v_mov_b32_e32 v5, v2
	v_mov_b32_e32 v3, v2
	v_mov_b64_e32 v[40:41], v[4:5]
	v_mov_b64_e32 v[38:39], v[2:3]
	s_and_saveexec_b64 s[12:13], vcc
	s_cbranch_execz .LBB0_775
	v_xor_b32_e32 v38, 0x820, v76
	v_ashrrev_i32_e32 v39, 31, v38
	v_lshlrev_b64 v[38:39], 14, v[38:39]
	v_lshl_add_u64 v[38:39], v[78:79], 0, v[38:39]
	global_load_dwordx4 v[38:41], v[38:39], off nt
.LBB0_775:
	s_or_b64 exec, exec, s[12:13]
	v_mov_b64_e32 v[44:45], v[4:5]
	v_mov_b64_e32 v[42:43], v[2:3]
	s_and_saveexec_b64 s[12:13], vcc
	s_cbranch_execz .LBB0_777
	v_xor_b32_e32 v4, 0x821, v76
	v_ashrrev_i32_e32 v5, 31, v4
	v_lshlrev_b64 v[4:5], 14, v[4:5]
	v_lshl_add_u64 v[4:5], v[78:79], 0, v[4:5]
	global_load_dwordx4 v[42:45], v[4:5], off nt
.LBB0_777:
	s_or_b64 exec, exec, s[12:13]
	v_mov_b32_e32 v4, v2
	v_mov_b32_e32 v5, v2
	v_mov_b32_e32 v3, v2
	v_mov_b64_e32 v[48:49], v[4:5]
	v_mov_b64_e32 v[46:47], v[2:3]
	s_and_saveexec_b64 s[12:13], vcc
	s_cbranch_execz .LBB0_779
	v_xor_b32_e32 v46, 0x828, v76
	v_ashrrev_i32_e32 v47, 31, v46
	v_lshlrev_b64 v[46:47], 14, v[46:47]
	v_lshl_add_u64 v[46:47], v[78:79], 0, v[46:47]
	global_load_dwordx4 v[46:49], v[46:47], off nt
.LBB0_779:
	s_or_b64 exec, exec, s[12:13]
	v_mov_b64_e32 v[52:53], v[4:5]
	v_mov_b64_e32 v[50:51], v[2:3]
	s_and_saveexec_b64 s[12:13], vcc
	s_cbranch_execz .LBB0_781
	v_xor_b32_e32 v4, 0x829, v76
	v_ashrrev_i32_e32 v5, 31, v4
	v_lshlrev_b64 v[4:5], 14, v[4:5]
	v_lshl_add_u64 v[4:5], v[78:79], 0, v[4:5]
	global_load_dwordx4 v[50:53], v[4:5], off nt
.LBB0_781:
	s_or_b64 exec, exec, s[12:13]
	v_mov_b32_e32 v4, v2
	v_mov_b32_e32 v5, v2
	v_mov_b32_e32 v3, v2
	v_mov_b64_e32 v[56:57], v[4:5]
	v_mov_b64_e32 v[54:55], v[2:3]
	s_and_saveexec_b64 s[12:13], vcc
	s_cbranch_execz .LBB0_783
	v_xor_b32_e32 v54, 0x830, v76
	v_ashrrev_i32_e32 v55, 31, v54
	v_lshlrev_b64 v[54:55], 14, v[54:55]
	v_lshl_add_u64 v[54:55], v[78:79], 0, v[54:55]
	global_load_dwordx4 v[54:57], v[54:55], off nt
.LBB0_783:
	s_or_b64 exec, exec, s[12:13]
	v_mov_b64_e32 v[60:61], v[4:5]
	v_mov_b64_e32 v[58:59], v[2:3]
	s_and_saveexec_b64 s[12:13], vcc
	s_cbranch_execz .LBB0_785
	v_xor_b32_e32 v4, 0x831, v76
	v_ashrrev_i32_e32 v5, 31, v4
	v_lshlrev_b64 v[4:5], 14, v[4:5]
	v_lshl_add_u64 v[4:5], v[78:79], 0, v[4:5]
	global_load_dwordx4 v[58:61], v[4:5], off nt
.LBB0_785:
	s_or_b64 exec, exec, s[12:13]
	v_mov_b32_e32 v4, v2
	v_mov_b32_e32 v5, v2
	v_mov_b32_e32 v3, v2
	v_mov_b64_e32 v[64:65], v[4:5]
	v_mov_b64_e32 v[62:63], v[2:3]
	s_and_saveexec_b64 s[12:13], vcc
	s_cbranch_execz .LBB0_787
	v_xor_b32_e32 v62, 0x838, v76
	v_ashrrev_i32_e32 v63, 31, v62
	v_lshlrev_b64 v[62:63], 14, v[62:63]
	v_lshl_add_u64 v[62:63], v[78:79], 0, v[62:63]
	global_load_dwordx4 v[62:65], v[62:63], off nt
.LBB0_787:
	s_or_b64 exec, exec, s[12:13]
	v_mov_b64_e32 v[68:69], v[4:5]
	v_mov_b64_e32 v[66:67], v[2:3]
	s_and_saveexec_b64 s[12:13], vcc
	s_cbranch_execz .LBB0_789
	v_xor_b32_e32 v4, 0x839, v76
	v_ashrrev_i32_e32 v5, 31, v4
	v_lshlrev_b64 v[4:5], 14, v[4:5]
	v_lshl_add_u64 v[4:5], v[78:79], 0, v[4:5]
	global_load_dwordx4 v[66:69], v[4:5], off nt

; __device__ __forceinline__ void ph_transpose_q8(const TrJob job, LAS unsigned* scr, int gw, int NGW, int lane) {
;     ...
;         f32x4 v[4][4];
; #pragma unroll
;         for (int i = 0; i < 4; ++i) { const int kq = 4 * i + (lane >> 4);
; #pragma unroll
;             for (int q = 0; q < 4; ++q) { const int k = k0 + 4 * kq + q; f32x4 t = {0.f, 0.f, 0.f, 0.f};
;                 if (inb) t = *(const f32x4*)(W + (size_t)k * job.N + sb + n4);
;                 v[i][q] = t; } }
.LBB0_844:
	s_or_b64 exec, exec, s[28:29]
	s_lshl_b32 s8, s1, 6
	v_or_b32_e32 v76, s8, v95
	v_lshl_add_u64 v[78:79], v[4:5], 2, v[68:69]
	v_mov_b32_e32 v3, 0
	v_mov_b32_e32 v4, 0
	v_mov_b32_e32 v5, 0
	s_and_saveexec_b64 s[10:11], s[6:7]
	s_cbranch_execz .LBB0_846
	v_mad_i64_i32 v[2:3], s[12:13], v76, s40, v[78:79]
	global_load_dwordx4 v[2:5], v[2:3], off nt
.LBB0_846:
	s_or_b64 exec, exec, s[10:11]
	v_mov_b32_e32 v6, 0
	v_or_b32_e32 v82, 1, v76
	v_mov_b32_e32 v10, 0
	v_mov_b32_e32 v11, 0
	v_mov_b32_e32 v12, 0
	v_mov_b32_e32 v13, 0
	s_and_saveexec_b64 s[10:11], s[6:7]
	s_cbranch_execz .LBB0_848
	v_mad_i64_i32 v[8:9], s[12:13], v82, s40, v[78:79]
	global_load_dwordx4 v[10:13], v[8:9], off nt
.LBB0_848:
	s_or_b64 exec, exec, s[10:11]
	v_or_b32_e32 v84, 2, v76
	v_mov_b32_e32 v7, 0
	v_mov_b32_e32 v8, 0
	v_mov_b32_e32 v9, 0
	s_and_saveexec_b64 s[10:11], s[6:7]
	s_cbranch_execz .LBB0_850
	v_mad_i64_i32 v[6:7], s[12:13], v84, s40, v[78:79]
	global_load_dwordx4 v[6:9], v[6:7], off nt
.LBB0_850:
	s_or_b64 exec, exec, s[10:11]
	v_mov_b32_e32 v14, 0
	v_or_b32_e32 v86, 3, v76
	v_mov_b32_e32 v18, 0
	v_mov_b32_e32 v19, 0
	v_mov_b32_e32 v20, 0
	v_mov_b32_e32 v21, 0
	s_and_saveexec_b64 s[10:11], s[6:7]
	s_cbranch_execz .LBB0_852
	v_mad_i64_i32 v[16:17], s[12:13], v86, s40, v[78:79]
	global_load_dwordx4 v[18:21], v[16:17], off nt
.LBB0_852:
	s_or_b64 exec, exec, s[10:11]
	v_or_b32_e32 v88, 16, v76
	v_mov_b32_e32 v15, 0
	v_mov_b32_e32 v16, 0
	v_mov_b32_e32 v17, 0
	s_and_saveexec_b64 s[10:11], s[6:7]
	s_cbranch_execz .LBB0_854
	v_mad_i64_i32 v[14:15], s[12:13], v88, s40, v[78:79]
	global_load_dwordx4 v[14:17], v[14:15], off nt
.LBB0_854:
	s_or_b64 exec, exec, s[10:11]
	v_mov_b32_e32 v22, 0
	v_or_b32_e32 v90, 17, v76
	v_mov_b32_e32 v26, 0
	v_mov_b32_e32 v27, 0
	v_mov_b32_e32 v28, 0
	v_mov_b32_e32 v29, 0
	s_and_saveexec_b64 s[10:11], s[6:7]
	s_cbranch_execz .LBB0_856
	v_mad_i64_i32 v[24:25], s[12:13], v90, s40, v[78:79]
	global_load_dwordx4 v[26:29], v[24:25], off nt
.LBB0_856:
	s_or_b64 exec, exec, s[10:11]
	v_or_b32_e32 v92, 18, v76
	v_mov_b32_e32 v23, 0
	v_mov_b32_e32 v24, 0
	v_mov_b32_e32 v25, 0
	s_and_saveexec_b64 s[10:11], s[6:7]
	s_cbranch_execz .LBB0_858
	v_mad_i64_i32 v[22:23], s[12:13], v92, s40, v[78:79]
	global_load_dwordx4 v[22:25], v[22:23], off nt
.LBB0_858:
	s_or_b64 exec, exec, s[10:11]
	v_mov_b32_e32 v30, 0
	v_or_b32_e32 v94, 19, v76
	v_mov_b32_e32 v34, 0
	v_mov_b32_e32 v35, 0
	v_mov_b32_e32 v36, 0
	v_mov_b32_e32 v37, 0
	s_and_saveexec_b64 s[10:11], s[6:7]
	s_cbranch_execz .LBB0_860
	v_mad_i64_i32 v[32:33], s[12:13], v94, s40, v[78:79]
	global_load_dwordx4 v[34:37], v[32:33], off nt
.LBB0_860:
	s_or_b64 exec, exec, s[10:11]
	v_or_b32_e32 v96, 32, v76
	v_mov_b32_e32 v31, 0
	v_mov_b32_e32 v32, 0
	v_mov_b32_e32 v33, 0
	s_and_saveexec_b64 s[10:11], s[6:7]
	s_cbranch_execz .LBB0_862
	v_mad_i64_i32 v[30:31], s[12:13], v96, s40, v[78:79]
	global_load_dwordx4 v[30:33], v[30:31], off nt
.LBB0_862:
	s_or_b64 exec, exec, s[10:11]
	v_mov_b32_e32 v38, 0
	v_or_b32_e32 v98, 33, v76
	v_mov_b32_e32 v42, 0
	v_mov_b32_e32 v43, 0
	v_mov_b32_e32 v44, 0
	v_mov_b32_e32 v45, 0
	s_and_saveexec_b64 s[10:11], s[6:7]
	s_cbranch_execz .LBB0_864
	v_mad_i64_i32 v[40:41], s[12:13], v98, s40, v[78:79]
	global_load_dwordx4 v[42:45], v[40:41], off nt
.LBB0_864:
	s_or_b64 exec, exec, s[10:11]
	v_or_b32_e32 v100, 34, v76
	v_mov_b32_e32 v39, 0
	v_mov_b32_e32 v40, 0
	v_mov_b32_e32 v41, 0
	s_and_saveexec_b64 s[10:11], s[6:7]
	s_cbranch_execz .LBB0_866
	v_mad_i64_i32 v[38:39], s[12:13], v100, s40, v[78:79]
	global_load_dwordx4 v[38:41], v[38:39], off nt
.LBB0_866:
	s_or_b64 exec, exec, s[10:11]
	v_mov_b32_e32 v46, 0
	v_or_b32_e32 v102, 35, v76
	v_mov_b32_e32 v50, 0
	v_mov_b32_e32 v51, 0
	v_mov_b32_e32 v52, 0
	v_mov_b32_e32 v53, 0
	s_and_saveexec_b64 s[10:11], s[6:7]
	s_cbranch_execz .LBB0_868
	v_mad_i64_i32 v[48:49], s[12:13], v102, s40, v[78:79]
	global_load_dwordx4 v[50:53], v[48:49], off nt
.LBB0_868:
	s_or_b64 exec, exec, s[10:11]
	v_or_b32_e32 v103, 48, v76
	v_mov_b32_e32 v47, 0
	v_mov_b32_e32 v48, 0
	v_mov_b32_e32 v49, 0
	s_and_saveexec_b64 s[10:11], s[6:7]
	s_cbranch_execz .LBB0_870
	v_mad_i64_i32 v[46:47], s[12:13], v103, s40, v[78:79]
	global_load_dwordx4 v[46:49], v[46:47], off nt
.LBB0_870:
	s_or_b64 exec, exec, s[10:11]
	v_mov_b32_e32 v54, 0
	v_or_b32_e32 v105, 49, v76
	v_mov_b32_e32 v58, 0
	v_mov_b32_e32 v59, 0
	v_mov_b32_e32 v60, 0
	v_mov_b32_e32 v61, 0
	s_and_saveexec_b64 s[10:11], s[6:7]
	s_cbranch_execz .LBB0_872
	v_mad_i64_i32 v[56:57], s[12:13], v105, s40, v[78:79]
	global_load_dwordx4 v[58:61], v[56:57], off nt
.LBB0_872:
	s_or_b64 exec, exec, s[10:11]
	v_or_b32_e32 v106, 50, v76
	v_mov_b32_e32 v55, 0
	v_mov_b32_e32 v56, 0
	v_mov_b32_e32 v57, 0
	s_and_saveexec_b64 s[10:11], s[6:7]
	s_cbranch_execz .LBB0_874
	v_mad_i64_i32 v[54:55], s[12:13], v106, s40, v[78:79]
	global_load_dwordx4 v[54:57], v[54:55], off nt
.LBB0_874:
	s_or_b64 exec, exec, s[10:11]
	v_mov_b32_e32 v62, 0
	v_or_b32_e32 v107, 51, v76
	v_mov_b32_e32 v63, 0
	v_mov_b32_e32 v64, 0
	v_mov_b32_e32 v65, 0
	s_and_saveexec_b64 s[10:11], s[6:7]
	s_cbranch_execz .LBB0_876
	v_mad_i64_i32 v[62:63], s[6:7], v107, s40, v[78:79]
	global_load_dwordx4 v[62:65], v[62:63], off nt

; __device__ __forceinline__ void ph_transpose(const TrJob job, LAS unsigned* scr, int gw, int NGW, int lane) {
;     ...
;     for (int item = gw; item < nitems; item += NGW) {
;         const int kb = item / ngrp, gq = item % ngrp, k0 = 64 * kb, r0 = 64 * gq, sb = srcbase_of(job.kind, r0);
;         const int n4 = (lane & 15) * 4; const bool inb = sb + n4 < job.N;
;         f32x4 v[8][2];
; #pragma unroll
;         for (int i = 0; i < 8; ++i) { const int kp = 4 * i + (lane >> 4);
; #pragma unroll
;             for (int q = 0; q < 2; ++q) { const int k = k0 + 2 * kp + q; f32x4 t = {0.f, 0.f, 0.f, 0.f};
;                 if (inb) t = *(const f32x4*)(W + (size_t)(k ^ job.kxor) * job.N + sb + n4);
;                 v[i][q] = t; } }
.LBB0_919:
	s_ashr_i32 s6, s16, 31
	s_lshr_b32 s6, s6, 26
	s_add_i32 s6, s16, s6
	s_ashr_i32 s18, s6, 6
	s_lshl_b32 s17, s18, 12
	s_sub_i32 s8, s1, s17
	s_andn2_b32 s6, s6, 63
	v_add_u32_e32 v2, s8, v76
	s_ashr_i32 s9, s8, 31
	v_cmp_gt_i32_e32 vcc, s12, v2
	v_or_b32_e32 v74, s6, v77
	v_lshl_add_u64 v[72:73], s[8:9], 2, v[68:69]
	v_mov_b32_e32 v2, 0
	v_mov_b32_e32 v3, 0
	v_mov_b32_e32 v4, 0
	v_mov_b32_e32 v5, 0
	s_and_saveexec_b64 s[8:9], vcc
	s_cbranch_execz .LBB0_921
	v_ashrrev_i32_e32 v75, 31, v74
	v_lshlrev_b64 v[2:3], 14, v[74:75]
	v_lshl_add_u64 v[2:3], v[72:73], 0, v[2:3]
	global_load_dwordx4 v[2:5], v[2:3], off nt
.LBB0_921:
	s_or_b64 exec, exec, s[8:9]
	v_mov_b32_e32 v6, 0
	v_mov_b32_e32 v10, 0
	v_mov_b32_e32 v11, 0
	v_mov_b32_e32 v12, 0
	v_mov_b32_e32 v13, 0
	s_and_saveexec_b64 s[8:9], vcc
	s_cbranch_execz .LBB0_923
	v_or_b32_e32 v8, 1, v74
	v_ashrrev_i32_e32 v9, 31, v8
	v_lshlrev_b64 v[8:9], 14, v[8:9]
	v_lshl_add_u64 v[8:9], v[72:73], 0, v[8:9]
	global_load_dwordx4 v[10:13], v[8:9], off nt
.LBB0_923:
	s_or_b64 exec, exec, s[8:9]
	v_mov_b32_e32 v7, 0
	v_mov_b32_e32 v8, 0
	v_mov_b32_e32 v9, 0
	s_and_saveexec_b64 s[8:9], vcc
	s_cbranch_execz .LBB0_925
	v_or_b32_e32 v6, 8, v74
	v_ashrrev_i32_e32 v7, 31, v6
	v_lshlrev_b64 v[6:7], 14, v[6:7]
	v_lshl_add_u64 v[6:7], v[72:73], 0, v[6:7]
	global_load_dwordx4 v[6:9], v[6:7], off nt
.LBB0_925:
	s_or_b64 exec, exec, s[8:9]
	v_mov_b32_e32 v14, 0
	v_mov_b32_e32 v18, 0
	v_mov_b32_e32 v19, 0
	v_mov_b32_e32 v20, 0
	v_mov_b32_e32 v21, 0
	s_and_saveexec_b64 s[8:9], vcc
	s_cbranch_execz .LBB0_927
	v_or_b32_e32 v16, 9, v74
	v_ashrrev_i32_e32 v17, 31, v16
	v_lshlrev_b64 v[16:17], 14, v[16:17]
	v_lshl_add_u64 v[16:17], v[72:73], 0, v[16:17]
	global_load_dwordx4 v[18:21], v[16:17], off nt
.LBB0_927:
	s_or_b64 exec, exec, s[8:9]
	v_mov_b32_e32 v15, 0
	v_mov_b32_e32 v16, 0
	v_mov_b32_e32 v17, 0
	s_and_saveexec_b64 s[8:9], vcc
	s_cbranch_execz .LBB0_929
	v_or_b32_e32 v14, 16, v74
	v_ashrrev_i32_e32 v15, 31, v14
	v_lshlrev_b64 v[14:15], 14, v[14:15]
	v_lshl_add_u64 v[14:15], v[72:73], 0, v[14:15]
	global_load_dwordx4 v[14:17], v[14:15], off nt
.LBB0_929:
	s_or_b64 exec, exec, s[8:9]
	v_mov_b32_e32 v22, 0
	v_mov_b32_e32 v26, 0
	v_mov_b32_e32 v27, 0
	v_mov_b32_e32 v28, 0
	v_mov_b32_e32 v29, 0
	s_and_saveexec_b64 s[8:9], vcc
	s_cbranch_execz .LBB0_931
	v_or_b32_e32 v24, 17, v74
	v_ashrrev_i32_e32 v25, 31, v24
	v_lshlrev_b64 v[24:25], 14, v[24:25]
	v_lshl_add_u64 v[24:25], v[72:73], 0, v[24:25]
	global_load_dwordx4 v[26:29], v[24:25], off nt
.LBB0_931:
	s_or_b64 exec, exec, s[8:9]
	v_mov_b32_e32 v23, 0
	v_mov_b32_e32 v24, 0
	v_mov_b32_e32 v25, 0
	s_and_saveexec_b64 s[8:9], vcc
	s_cbranch_execz .LBB0_933
	v_or_b32_e32 v22, 24, v74
	v_ashrrev_i32_e32 v23, 31, v22
	v_lshlrev_b64 v[22:23], 14, v[22:23]
	v_lshl_add_u64 v[22:23], v[72:73], 0, v[22:23]
	global_load_dwordx4 v[22:25], v[22:23], off nt
.LBB0_933:
	s_or_b64 exec, exec, s[8:9]
	v_mov_b32_e32 v30, 0
	v_mov_b32_e32 v34, 0
	v_mov_b32_e32 v35, 0
	v_mov_b32_e32 v36, 0
	v_mov_b32_e32 v37, 0
	s_and_saveexec_b64 s[8:9], vcc
	s_cbranch_execz .LBB0_935
	v_or_b32_e32 v32, 25, v74
	v_ashrrev_i32_e32 v33, 31, v32
	v_lshlrev_b64 v[32:33], 14, v[32:33]
	v_lshl_add_u64 v[32:33], v[72:73], 0, v[32:33]
	global_load_dwordx4 v[34:37], v[32:33], off nt
.LBB0_935:
	s_or_b64 exec, exec, s[8:9]
	v_mov_b32_e32 v31, 0
	v_mov_b32_e32 v32, 0
	v_mov_b32_e32 v33, 0
	s_and_saveexec_b64 s[8:9], vcc
	s_cbranch_execz .LBB0_937
	v_or_b32_e32 v30, 32, v74
	v_ashrrev_i32_e32 v31, 31, v30
	v_lshlrev_b64 v[30:31], 14, v[30:31]
	v_lshl_add_u64 v[30:31], v[72:73], 0, v[30:31]
	global_load_dwordx4 v[30:33], v[30:31], off nt
.LBB0_937:
	s_or_b64 exec, exec, s[8:9]
	v_mov_b32_e32 v38, 0
	v_mov_b32_e32 v42, 0
	v_mov_b32_e32 v43, 0
	v_mov_b32_e32 v44, 0
	v_mov_b32_e32 v45, 0
	s_and_saveexec_b64 s[8:9], vcc
	s_cbranch_execz .LBB0_939
	v_or_b32_e32 v40, 33, v74
	v_ashrrev_i32_e32 v41, 31, v40
	v_lshlrev_b64 v[40:41], 14, v[40:41]
	v_lshl_add_u64 v[40:41], v[72:73], 0, v[40:41]
	global_load_dwordx4 v[42:45], v[40:41], off nt
.LBB0_939:
	s_or_b64 exec, exec, s[8:9]
	v_mov_b32_e32 v39, 0
	v_mov_b32_e32 v40, 0
	v_mov_b32_e32 v41, 0
	s_and_saveexec_b64 s[8:9], vcc
	s_cbranch_execz .LBB0_941
	v_or_b32_e32 v38, 40, v74
	v_ashrrev_i32_e32 v39, 31, v38
	v_lshlrev_b64 v[38:39], 14, v[38:39]
	v_lshl_add_u64 v[38:39], v[72:73], 0, v[38:39]
	global_load_dwordx4 v[38:41], v[38:39], off nt
.LBB0_941:
	s_or_b64 exec, exec, s[8:9]
	v_mov_b32_e32 v46, 0
	v_mov_b32_e32 v50, 0
	v_mov_b32_e32 v51, 0
	v_mov_b32_e32 v52, 0
	v_mov_b32_e32 v53, 0
	s_and_saveexec_b64 s[8:9], vcc
	s_cbranch_execz .LBB0_943
	v_or_b32_e32 v48, 41, v74
	v_ashrrev_i32_e32 v49, 31, v48
	v_lshlrev_b64 v[48:49], 14, v[48:49]
	v_lshl_add_u64 v[48:49], v[72:73], 0, v[48:49]
	global_load_dwordx4 v[50:53], v[48:49], off nt
.LBB0_943:
	s_or_b64 exec, exec, s[8:9]
	v_mov_b32_e32 v47, 0
	v_mov_b32_e32 v48, 0
	v_mov_b32_e32 v49, 0
	s_and_saveexec_b64 s[8:9], vcc
	s_cbranch_execz .LBB0_945
	v_or_b32_e32 v46, 48, v74
	v_ashrrev_i32_e32 v47, 31, v46
	v_lshlrev_b64 v[46:47], 14, v[46:47]
	v_lshl_add_u64 v[46:47], v[72:73], 0, v[46:47]
	global_load_dwordx4 v[46:49], v[46:47], off nt
.LBB0_945:
	s_or_b64 exec, exec, s[8:9]
	v_mov_b32_e32 v54, 0
	v_mov_b32_e32 v60, 0
	v_mov_b32_e32 v61, 0
	v_mov_b32_e32 v62, 0
	v_mov_b32_e32 v63, 0
	s_and_saveexec_b64 s[8:9], vcc
	s_cbranch_execz .LBB0_947
	v_or_b32_e32 v56, 49, v74
	v_ashrrev_i32_e32 v57, 31, v56
	v_lshlrev_b64 v[56:57], 14, v[56:57]
	v_lshl_add_u64 v[56:57], v[72:73], 0, v[56:57]
	global_load_dwordx4 v[60:63], v[56:57], off nt
.LBB0_947:
	s_or_b64 exec, exec, s[8:9]
	v_mov_b32_e32 v55, 0
	v_mov_b32_e32 v56, 0
	v_mov_b32_e32 v57, 0
	s_and_saveexec_b64 s[8:9], vcc
	s_cbranch_execz .LBB0_949
	v_or_b32_e32 v54, 56, v74
	v_ashrrev_i32_e32 v55, 31, v54
	v_lshlrev_b64 v[54:55], 14, v[54:55]
	v_lshl_add_u64 v[54:55], v[72:73], 0, v[54:55]
	global_load_dwordx4 v[54:57], v[54:55], off nt
.LBB0_949:
	s_or_b64 exec, exec, s[8:9]
	v_mov_b32_e32 v58, 0
	v_mov_b32_e32 v64, 0
	v_mov_b32_e32 v65, 0
	v_mov_b32_e32 v66, 0
	v_mov_b32_e32 v67, 0
	s_and_saveexec_b64 s[8:9], vcc
	s_cbranch_execz .LBB0_951
	v_or_b32_e32 v64, 57, v74
	v_ashrrev_i32_e32 v65, 31, v64
	v_lshlrev_b64 v[64:65], 14, v[64:65]
	v_lshl_add_u64 v[64:65], v[72:73], 0, v[64:65]
	global_load_dwordx4 v[64:67], v[64:65], off nt

; __device__ __forceinline__ void ph_transpose_q8(const TrJob job, LAS unsigned* scr, int gw, int NGW, int lane) {
;     ...
;     for (int item = gw; item < nitems; item += NGW) {
;         const int kb = item / ngrp, gq = item % ngrp, k0 = 64 * kb, r0 = 64 * gq, sb = srcbase_of(job.kind, r0);
;         const int n4 = (lane & 15) * 4; const bool inb = sb + n4 < job.N;
;         f32x4 isc = {0.f, 0.f, 0.f, 0.f};
;         if (inb) { const f32x4 cm = *(const f32x4*)(job.qmax + sb + n4);
; #pragma unroll
;             for (int e = 0; e < 4; ++e) isc[e] = cm[e] > 0.f ? 127.f / cm[e] : 0.f; }
;         f32x4 v[4][4];
; #pragma unroll
;         for (int i = 0; i < 4; ++i) { const int kq = 4 * i + (lane >> 4);
; #pragma unroll
;             for (int q = 0; q < 4; ++q) { const int k = k0 + 4 * kq + q; f32x4 t = {0.f, 0.f, 0.f, 0.f};
;                 if (inb) t = *(const f32x4*)(W + (size_t)k * job.N + sb + n4);
;                 v[i][q] = t; } }
;     ...
;               for (int q = 0; q < 4; ++q) v[i][q] = v[i][q] * isc * kv[i][q]; }
.LBB0_970:
	s_ashr_i32 s6, s3, 31
	s_lshr_b32 s6, s6, 26
	s_add_i32 s6, s3, s6
	s_lshl_b32 s7, s6, 6
	s_and_b32 s17, s7, 0xfffff000
	s_sub_i32 s8, s4, s17
	s_ashr_i32 s9, s8, 31
	s_lshl_b64 s[10:11], s[8:9], 2
	v_lshl_add_u64 v[2:3], v[8:9], 0, s[10:11]
	global_load_dwordx4 v[2:5], v[2:3], off
	s_andn2_b32 s6, s6, 63
	v_or_b32_e32 v6, s6, v18
	v_ashrrev_i32_e32 v7, 31, v6
	v_or_b32_e32 v14, 1, v6
	v_or_b32_e32 v16, 2, v6
	v_or_b32_e32 v28, 3, v6
	v_or_b32_e32 v30, 16, v6
	v_or_b32_e32 v32, 17, v6
	v_or_b32_e32 v34, 18, v6
	v_or_b32_e32 v36, 19, v6
	v_or_b32_e32 v38, 32, v6
	v_or_b32_e32 v40, 33, v6
	v_or_b32_e32 v42, 34, v6
	v_or_b32_e32 v44, 35, v6
	v_or_b32_e32 v46, 48, v6
	v_or_b32_e32 v48, 49, v6
	v_or_b32_e32 v50, 50, v6
	v_lshlrev_b64 v[52:53], 14, v[6:7]
	v_ashrrev_i32_e32 v15, 31, v14
	v_ashrrev_i32_e32 v17, 31, v16
	v_ashrrev_i32_e32 v29, 31, v28
	v_ashrrev_i32_e32 v31, 31, v30
	v_ashrrev_i32_e32 v33, 31, v32
	v_ashrrev_i32_e32 v35, 31, v34
	v_ashrrev_i32_e32 v37, 31, v36
	v_ashrrev_i32_e32 v39, 31, v38
	v_ashrrev_i32_e32 v41, 31, v40
	v_ashrrev_i32_e32 v43, 31, v42
	v_ashrrev_i32_e32 v45, 31, v44
	v_ashrrev_i32_e32 v47, 31, v46
	v_ashrrev_i32_e32 v49, 31, v48
	v_lshl_add_u64 v[86:87], v[10:11], 0, s[10:11]
	v_ashrrev_i32_e32 v51, 31, v50
	v_lshlrev_b64 v[14:15], 14, v[14:15]
	v_lshlrev_b64 v[16:17], 14, v[16:17]
	v_lshlrev_b64 v[28:29], 14, v[28:29]
	v_lshlrev_b64 v[30:31], 14, v[30:31]
	v_lshlrev_b64 v[32:33], 14, v[32:33]
	v_lshlrev_b64 v[34:35], 14, v[34:35]
	v_lshlrev_b64 v[36:37], 14, v[36:37]
	v_lshlrev_b64 v[38:39], 14, v[38:39]
	v_lshlrev_b64 v[40:41], 14, v[40:41]
	v_lshlrev_b64 v[42:43], 14, v[42:43]
	v_lshlrev_b64 v[44:45], 14, v[44:45]
	v_lshlrev_b64 v[46:47], 14, v[46:47]
	v_lshlrev_b64 v[48:49], 14, v[48:49]
	v_lshl_add_u64 v[82:83], v[86:87], 0, v[52:53]
	v_lshlrev_b64 v[80:81], 14, v[50:51]
	v_lshl_add_u64 v[88:89], v[86:87], 0, v[14:15]
	v_lshl_add_u64 v[90:91], v[86:87], 0, v[16:17]
	v_lshl_add_u64 v[92:93], v[86:87], 0, v[28:29]
	v_lshl_add_u64 v[94:95], v[86:87], 0, v[30:31]
	v_lshl_add_u64 v[96:97], v[86:87], 0, v[32:33]
	v_lshl_add_u64 v[98:99], v[86:87], 0, v[34:35]
	v_lshl_add_u64 v[100:101], v[86:87], 0, v[36:37]
	v_lshl_add_u64 v[102:103], v[86:87], 0, v[38:39]
	v_lshl_add_u64 v[104:105], v[86:87], 0, v[40:41]
	v_lshl_add_u64 v[106:107], v[86:87], 0, v[42:43]
	v_lshl_add_u64 v[108:109], v[86:87], 0, v[44:45]
	v_lshl_add_u64 v[110:111], v[86:87], 0, v[46:47]
	v_lshl_add_u64 v[112:113], v[86:87], 0, v[48:49]
	global_load_dwordx4 v[14:17], v[82:83], off nt
	global_load_dwordx4 v[28:31], v[88:89], off nt
	global_load_dwordx4 v[32:35], v[90:91], off nt
	global_load_dwordx4 v[36:39], v[92:93], off nt
	global_load_dwordx4 v[40:43], v[94:95], off nt
	global_load_dwordx4 v[44:47], v[96:97], off nt
	global_load_dwordx4 v[48:51], v[98:99], off nt
	global_load_dwordx4 v[52:55], v[100:101], off nt
	global_load_dwordx4 v[56:59], v[102:103], off nt
	global_load_dwordx4 v[60:63], v[104:105], off nt
	global_load_dwordx4 v[64:67], v[106:107], off nt
	global_load_dwordx4 v[68:71], v[108:109], off nt
	global_load_dwordx4 v[72:75], v[110:111], off nt
	global_load_dwordx4 v[76:79], v[112:113], off nt
	v_lshl_add_u64 v[80:81], v[86:87], 0, v[80:81]
	v_or_b32_e32 v6, 51, v6
	s_waitcnt vmcnt(0)
	v_div_scale_f32 v7, s[10:11], v2, v2, s13
	v_rcp_f32_e32 v83, v7
	v_div_scale_f32 v82, vcc, s13, v2, s13
	v_div_scale_f32 v84, s[10:11], v3, v3, s13
	v_fma_f32 v88, -v7, v83, 1.0
	v_fmac_f32_e32 v83, v88, v83
	v_mul_f32_e32 v88, v82, v83
	v_fma_f32 v89, -v7, v88, v82
	v_fmac_f32_e32 v88, v89, v83
	v_fma_f32 v7, -v7, v88, v82
	v_div_fmas_f32 v90, v7, v83, v88
	global_load_dwordx4 v[80:83], v[80:81], off nt
	v_rcp_f32_e32 v91, v84
	v_ashrrev_i32_e32 v7, 31, v6
	v_lshlrev_b64 v[6:7], 14, v[6:7]
	v_lshl_add_u64 v[6:7], v[86:87], 0, v[6:7]
	global_load_dwordx4 v[86:89], v[6:7], off nt
	v_div_fixup_f32 v6, v90, v2, s13
	v_cmp_lt_f32_e32 vcc, 0, v2
	v_fma_f32 v2, -v84, v91, 1.0
	v_fmac_f32_e32 v91, v2, v91
	v_cndmask_b32_e32 v90, 0, v6, vcc
	v_div_scale_f32 v2, vcc, s13, v3, s13
	v_mul_f32_e32 v6, v2, v91
	v_fma_f32 v7, -v84, v6, v2
	v_fmac_f32_e32 v6, v7, v91
	v_fma_f32 v2, -v84, v6, v2
	v_div_fmas_f32 v2, v2, v91, v6
	v_div_scale_f32 v6, s[10:11], v4, v4, s13
	v_rcp_f32_e32 v7, v6
	v_div_fixup_f32 v2, v2, v3, s13
	v_cmp_lt_f32_e32 vcc, 0, v3
	s_nop 1
	v_cndmask_b32_e32 v91, 0, v2, vcc
	v_fma_f32 v2, -v6, v7, 1.0
	v_fmac_f32_e32 v7, v2, v7
	v_div_scale_f32 v2, vcc, s13, v4, s13
	v_mul_f32_e32 v3, v2, v7
	v_fma_f32 v84, -v6, v3, v2
	v_fmac_f32_e32 v3, v84, v7
	v_fma_f32 v2, -v6, v3, v2
	v_div_fmas_f32 v2, v2, v7, v3
	v_div_scale_f32 v3, s[10:11], v5, v5, s13
	v_rcp_f32_e32 v6, v3
	v_div_fixup_f32 v2, v2, v4, s13
	v_cmp_lt_f32_e32 vcc, 0, v4
	v_pk_mul_f32 v[28:29], v[90:91], v[28:29]
	v_pk_mul_f32 v[94:95], v[90:91], v[14:15]
	v_cndmask_b32_e32 v92, 0, v2, vcc
	v_fma_f32 v2, -v3, v6, 1.0
	v_fmac_f32_e32 v6, v2, v6
	v_div_scale_f32 v2, vcc, s13, v5, s13
	v_mul_f32_e32 v4, v2, v6
	v_fma_f32 v7, -v3, v4, v2
	v_fmac_f32_e32 v4, v7, v6
	v_fma_f32 v2, -v3, v4, v2
	v_div_fmas_f32 v2, v2, v6, v4
	v_div_fixup_f32 v2, v2, v5, s13
	v_cmp_lt_f32_e32 vcc, 0, v5
	v_med3_f32 v28, v28, s16, v20
	v_med3_f32 v29, v29, s16, v20
	v_cndmask_b32_e32 v93, 0, v2, vcc
	v_pk_mul_f32 v[32:33], v[90:91], v[32:33]
	v_rndne_f32_e32 v28, v28
	v_rndne_f32_e32 v29, v29
	v_pk_mul_f32 v[2:3], v[92:93], v[74:75]
	v_pk_mul_f32 v[74:75], v[90:91], v[76:77]
	v_med3_f32 v32, v32, s16, v20
	v_med3_f32 v33, v33, s16, v20
	v_cvt_i32_f32_e32 v28, v28
	v_cvt_i32_f32_e32 v29, v29
	v_pk_mul_f32 v[36:37], v[90:91], v[36:37]
	v_rndne_f32_e32 v32, v32
	v_rndne_f32_e32 v33, v33
	v_med3_f32 v36, v36, s16, v20
	v_med3_f32 v37, v37, s16, v20
	v_cvt_i32_f32_sdwa v32, v32 dst_sel:WORD_1 dst_unused:UNUSED_PAD src0_sel:DWORD
	v_cvt_i32_f32_sdwa v33, v33 dst_sel:WORD_1 dst_unused:UNUSED_PAD src0_sel:DWORD
	v_rndne_f32_e32 v36, v36
	v_rndne_f32_e32 v37, v37
	v_cvt_i32_f32_sdwa v36, v36 dst_sel:BYTE_3 dst_unused:UNUSED_PAD src0_sel:DWORD
	v_cvt_i32_f32_sdwa v37, v37 dst_sel:BYTE_3 dst_unused:UNUSED_PAD src0_sel:DWORD
	v_lshlrev_b32_e32 v29, 8, v29
	v_lshlrev_b32_e32 v28, 8, v28
	s_waitcnt vmcnt(1)
; __device__ __forceinline__ void ph_transpose_q8(const TrJob job, LAS unsigned* scr, int gw, int NGW, int lane) {
;     ...
;         for (int i = 0; i < 4; ++i) { const int kq = 4 * i + (lane >> 4);
; #pragma unroll
;             for (int e = 0; e < 4; ++e) { const int b0 = (int)rintf(fminf(fmaxf(v[i][0][e], -127.f), 127.f)), b1 = (int)rintf(fminf(fmaxf(v[i][1][e], -127.f), 127.f)), b2 = (int)rintf(fminf(fmaxf(v[i][2][e], -127.f), 127.f)), b3 = (int)rintf(fminf(fmaxf(v[i][3][e], -127.f), 127.f));
;                 scr[kq * 65 + n4 + e] = (unsigned)(b0 & 255) | ((unsigned)(b1 & 255) << 8) | ((unsigned)(b2 & 255) << 16) | ((unsigned)b3 << 24); } }
	v_pk_mul_f32 v[76:77], v[90:91], v[80:81]
	v_med3_f32 v80, v94, s16, v20
	v_med3_f32 v81, v95, s16, v20
	v_rndne_f32_e32 v80, v80
	v_rndne_f32_e32 v81, v81
	v_cvt_i32_f32_e32 v81, v81
	v_cvt_i32_f32_e32 v80, v80
	v_and_b32_e32 v29, 0xff00, v29
	v_and_b32_e32 v28, 0xff00, v28
	v_or_b32_sdwa v29, v29, v81 dst_sel:DWORD dst_unused:UNUSED_PAD src0_sel:DWORD src1_sel:BYTE_0
	v_or_b32_sdwa v28, v28, v80 dst_sel:DWORD dst_unused:UNUSED_PAD src0_sel:DWORD src1_sel:BYTE_0
	v_and_b32_e32 v33, 0xff0000, v33
	v_and_b32_e32 v32, 0xff0000, v32
	v_or_b32_e32 v29, v29, v33
	v_or_b32_e32 v28, v28, v32
	v_pk_mul_f32 v[30:31], v[92:93], v[30:31]
	v_or_b32_e32 v29, v29, v37
	v_or_b32_e32 v28, v28, v36
	ds_write2_b32 v21, v28, v29 offset1:1
	v_med3_f32 v28, v30, s16, v20
	v_med3_f32 v31, v31, s16, v20
	v_pk_mul_f32 v[16:17], v[92:93], v[16:17]
	v_pk_mul_f32 v[34:35], v[92:93], v[34:35]
	v_rndne_f32_e32 v28, v28
	v_rndne_f32_e32 v31, v31
	v_med3_f32 v16, v16, s16, v20
	v_med3_f32 v29, v34, s16, v20
	v_med3_f32 v17, v17, s16, v20
	v_med3_f32 v32, v35, s16, v20
	v_cvt_i32_f32_e32 v28, v28
	v_cvt_i32_f32_e32 v31, v31
	v_pk_mul_f32 v[38:39], v[92:93], v[38:39]
	v_rndne_f32_e32 v16, v16
	v_rndne_f32_e32 v29, v29
	v_rndne_f32_e32 v17, v17
	v_rndne_f32_e32 v32, v32
	v_med3_f32 v30, v38, s16, v20
	v_med3_f32 v33, v39, s16, v20
	v_cvt_i32_f32_e32 v17, v17
	v_cvt_i32_f32_e32 v16, v16
	v_cvt_i32_f32_sdwa v29, v29 dst_sel:WORD_1 dst_unused:UNUSED_PAD src0_sel:DWORD
	v_cvt_i32_f32_sdwa v32, v32 dst_sel:WORD_1 dst_unused:UNUSED_PAD src0_sel:DWORD
	v_rndne_f32_e32 v30, v30
	v_rndne_f32_e32 v33, v33
	v_cvt_i32_f32_sdwa v30, v30 dst_sel:BYTE_3 dst_unused:UNUSED_PAD src0_sel:DWORD
	v_cvt_i32_f32_sdwa v33, v33 dst_sel:BYTE_3 dst_unused:UNUSED_PAD src0_sel:DWORD
	v_lshlrev_b32_e32 v31, 8, v31
	v_lshlrev_b32_e32 v28, 8, v28
	v_and_b32_e32 v31, 0xff00, v31
	v_and_b32_e32 v28, 0xff00, v28
	v_or_b32_sdwa v17, v31, v17 dst_sel:DWORD dst_unused:UNUSED_PAD src0_sel:DWORD src1_sel:BYTE_0
	v_or_b32_sdwa v16, v28, v16 dst_sel:DWORD dst_unused:UNUSED_PAD src0_sel:DWORD src1_sel:BYTE_0
	v_and_b32_e32 v28, 0xff0000, v32
	v_and_b32_e32 v29, 0xff0000, v29
	v_or_b32_e32 v17, v17, v28
	v_or_b32_e32 v16, v16, v29
	v_pk_mul_f32 v[44:45], v[90:91], v[44:45]
	v_or_b32_e32 v17, v17, v33
	v_or_b32_e32 v16, v16, v30
	ds_write2_b32 v21, v16, v17 offset0:2 offset1:3
	v_med3_f32 v17, v44, s16, v20
	v_med3_f32 v31, v45, s16, v20
	v_pk_mul_f32 v[40:41], v[90:91], v[40:41]
	v_pk_mul_f32 v[48:49], v[90:91], v[48:49]
	v_rndne_f32_e32 v17, v17
	v_rndne_f32_e32 v31, v31
	v_med3_f32 v16, v40, s16, v20
	v_med3_f32 v28, v48, s16, v20
	v_med3_f32 v30, v41, s16, v20
	v_med3_f32 v32, v49, s16, v20
	v_cvt_i32_f32_e32 v17, v17
	v_cvt_i32_f32_e32 v31, v31
	v_pk_mul_f32 v[52:53], v[90:91], v[52:53]
	v_rndne_f32_e32 v16, v16
	v_rndne_f32_e32 v28, v28
	v_rndne_f32_e32 v30, v30
	v_rndne_f32_e32 v32, v32
	v_med3_f32 v29, v52, s16, v20
	v_med3_f32 v33, v53, s16, v20
	v_cvt_i32_f32_e32 v30, v30
	v_cvt_i32_f32_e32 v16, v16
	v_cvt_i32_f32_sdwa v28, v28 dst_sel:WORD_1 dst_unused:UNUSED_PAD src0_sel:DWORD
	v_cvt_i32_f32_sdwa v32, v32 dst_sel:WORD_1 dst_unused:UNUSED_PAD src0_sel:DWORD
	v_rndne_f32_e32 v29, v29
	v_rndne_f32_e32 v33, v33
	v_cvt_i32_f32_sdwa v29, v29 dst_sel:BYTE_3 dst_unused:UNUSED_PAD src0_sel:DWORD
	v_cvt_i32_f32_sdwa v33, v33 dst_sel:BYTE_3 dst_unused:UNUSED_PAD src0_sel:DWORD
	v_lshlrev_b32_e32 v31, 8, v31
	v_lshlrev_b32_e32 v17, 8, v17
	v_and_b32_e32 v31, 0xff00, v31
	v_and_b32_e32 v17, 0xff00, v17
	v_or_b32_sdwa v30, v31, v30 dst_sel:DWORD dst_unused:UNUSED_PAD src0_sel:DWORD src1_sel:BYTE_0
	v_or_b32_sdwa v16, v17, v16 dst_sel:DWORD dst_unused:UNUSED_PAD src0_sel:DWORD src1_sel:BYTE_0
	v_and_b32_e32 v17, 0xff0000, v32
	v_and_b32_e32 v28, 0xff0000, v28
	v_or_b32_e32 v17, v30, v17
	v_or_b32_e32 v16, v16, v28
	v_pk_mul_f32 v[46:47], v[92:93], v[46:47]
	v_or_b32_e32 v17, v17, v33
	v_or_b32_e32 v16, v16, v29
	ds_write2_b32 v22, v16, v17 offset1:1
	v_med3_f32 v17, v46, s16, v20
	v_med3_f32 v31, v47, s16, v20
	v_pk_mul_f32 v[42:43], v[92:93], v[42:43]
	v_pk_mul_f32 v[50:51], v[92:93], v[50:51]
	v_rndne_f32_e32 v17, v17
	v_rndne_f32_e32 v31, v31
	v_med3_f32 v16, v42, s16, v20
	v_med3_f32 v28, v50, s16, v20
	v_med3_f32 v30, v43, s16, v20
	v_med3_f32 v32, v51, s16, v20
	v_cvt_i32_f32_e32 v17, v17
	v_cvt_i32_f32_e32 v31, v31
	v_pk_mul_f32 v[54:55], v[92:93], v[54:55]
	v_rndne_f32_e32 v16, v16
	v_rndne_f32_e32 v28, v28
	v_rndne_f32_e32 v30, v30
	v_rndne_f32_e32 v32, v32
	v_med3_f32 v29, v54, s16, v20
	v_med3_f32 v33, v55, s16, v20
	v_cvt_i32_f32_e32 v30, v30
	v_cvt_i32_f32_e32 v16, v16
	v_cvt_i32_f32_sdwa v28, v28 dst_sel:WORD_1 dst_unused:UNUSED_PAD src0_sel:DWORD
	v_cvt_i32_f32_sdwa v32, v32 dst_sel:WORD_1 dst_unused:UNUSED_PAD src0_sel:DWORD
	v_rndne_f32_e32 v29, v29
	v_rndne_f32_e32 v33, v33
	v_cvt_i32_f32_sdwa v29, v29 dst_sel:BYTE_3 dst_unused:UNUSED_PAD src0_sel:DWORD
	v_cvt_i32_f32_sdwa v33, v33 dst_sel:BYTE_3 dst_unused:UNUSED_PAD src0_sel:DWORD
	v_lshlrev_b32_e32 v31, 8, v31
	v_lshlrev_b32_e32 v17, 8, v17
	v_and_b32_e32 v31, 0xff00, v31
	v_and_b32_e32 v17, 0xff00, v17
	v_or_b32_sdwa v30, v31, v30 dst_sel:DWORD dst_unused:UNUSED_PAD src0_sel:DWORD src1_sel:BYTE_0
	v_or_b32_sdwa v16, v17, v16 dst_sel:DWORD dst_unused:UNUSED_PAD src0_sel:DWORD src1_sel:BYTE_0
	v_and_b32_e32 v17, 0xff0000, v32
	v_and_b32_e32 v28, 0xff0000, v28
	v_or_b32_e32 v17, v30, v17
	v_or_b32_e32 v16, v16, v28
	v_pk_mul_f32 v[60:61], v[90:91], v[60:61]
	v_or_b32_e32 v17, v17, v33
	v_or_b32_e32 v16, v16, v29
	ds_write2_b32 v23, v16, v17 offset1:1
	v_med3_f32 v17, v60, s16, v20
	v_med3_f32 v31, v61, s16, v20
	v_pk_mul_f32 v[56:57], v[90:91], v[56:57]
; __device__ __forceinline__ void ph_transpose_q8(const TrJob job, LAS unsigned* scr, int gw, int NGW, int lane) {
;     ...
;         for (int i = 0; i < 4; ++i) { const int kq = 4 * i + (lane >> 4);
; #pragma unroll
;             for (int e = 0; e < 4; ++e) { const int b0 = (int)rintf(fminf(fmaxf(v[i][0][e], -127.f), 127.f)), b1 = (int)rintf(fminf(fmaxf(v[i][1][e], -127.f), 127.f)), b2 = (int)rintf(fminf(fmaxf(v[i][2][e], -127.f), 127.f)), b3 = (int)rintf(fminf(fmaxf(v[i][3][e], -127.f), 127.f));
;                 scr[kq * 65 + n4 + e] = (unsigned)(b0 & 255) | ((unsigned)(b1 & 255) << 8) | ((unsigned)(b2 & 255) << 16) | ((unsigned)b3 << 24); } }
;         asm volatile("s_waitcnt lgkmcnt(0)" ::: "memory");
;         const int c = lane & 3;
; #pragma unroll
;         for (int j = 0; j < 4; ++j) { const int n = (lane >> 2) + 16 * j; const int sc = colmap(job.kind, r0 + n) - sb;
;             u32x4 o = {0u, 0u, 0u, 0u};
;             if (sc >= 0) { o.x = scr[(4 * c + 0) * 65 + sc]; o.y = scr[(4 * c + 1) * 65 + sc]; o.z = scr[(4 * c + 2) * 65 + sc]; o.w = scr[(4 * c + 3) * 65 + sc]; }
	v_pk_mul_f32 v[64:65], v[90:91], v[64:65]
	v_rndne_f32_e32 v17, v17
	v_rndne_f32_e32 v31, v31
	v_med3_f32 v16, v56, s16, v20
	v_med3_f32 v28, v64, s16, v20
	v_med3_f32 v30, v57, s16, v20
	v_med3_f32 v32, v65, s16, v20
	v_cvt_i32_f32_e32 v17, v17
	v_cvt_i32_f32_e32 v31, v31
	v_pk_mul_f32 v[68:69], v[90:91], v[68:69]
	v_rndne_f32_e32 v16, v16
	v_rndne_f32_e32 v28, v28
	v_rndne_f32_e32 v30, v30
	v_rndne_f32_e32 v32, v32
	v_med3_f32 v29, v68, s16, v20
	v_med3_f32 v33, v69, s16, v20
	v_cvt_i32_f32_e32 v30, v30
	v_cvt_i32_f32_e32 v16, v16
	v_cvt_i32_f32_sdwa v28, v28 dst_sel:WORD_1 dst_unused:UNUSED_PAD src0_sel:DWORD
	v_cvt_i32_f32_sdwa v32, v32 dst_sel:WORD_1 dst_unused:UNUSED_PAD src0_sel:DWORD
	v_rndne_f32_e32 v29, v29
	v_rndne_f32_e32 v33, v33
	v_cvt_i32_f32_sdwa v29, v29 dst_sel:BYTE_3 dst_unused:UNUSED_PAD src0_sel:DWORD
	v_cvt_i32_f32_sdwa v33, v33 dst_sel:BYTE_3 dst_unused:UNUSED_PAD src0_sel:DWORD
	v_lshlrev_b32_e32 v31, 8, v31
	v_lshlrev_b32_e32 v17, 8, v17
	v_and_b32_e32 v31, 0xff00, v31
	v_and_b32_e32 v17, 0xff00, v17
	v_or_b32_sdwa v30, v31, v30 dst_sel:DWORD dst_unused:UNUSED_PAD src0_sel:DWORD src1_sel:BYTE_0
	v_or_b32_sdwa v16, v17, v16 dst_sel:DWORD dst_unused:UNUSED_PAD src0_sel:DWORD src1_sel:BYTE_0
	v_and_b32_e32 v17, 0xff0000, v32
	v_and_b32_e32 v28, 0xff0000, v28
	v_or_b32_e32 v17, v30, v17
	v_or_b32_e32 v16, v16, v28
	v_pk_mul_f32 v[62:63], v[92:93], v[62:63]
	v_or_b32_e32 v17, v17, v33
	v_or_b32_e32 v16, v16, v29
	ds_write2_b32 v24, v16, v17 offset1:1
	v_med3_f32 v17, v62, s16, v20
	v_med3_f32 v31, v63, s16, v20
	v_pk_mul_f32 v[58:59], v[92:93], v[58:59]
	v_pk_mul_f32 v[66:67], v[92:93], v[66:67]
	v_rndne_f32_e32 v17, v17
	v_rndne_f32_e32 v31, v31
	v_med3_f32 v16, v58, s16, v20
	v_med3_f32 v28, v66, s16, v20
	v_med3_f32 v30, v59, s16, v20
	v_med3_f32 v32, v67, s16, v20
	v_cvt_i32_f32_e32 v17, v17
	v_cvt_i32_f32_e32 v31, v31
	v_pk_mul_f32 v[70:71], v[92:93], v[70:71]
	v_rndne_f32_e32 v16, v16
	v_rndne_f32_e32 v28, v28
	v_rndne_f32_e32 v30, v30
	v_rndne_f32_e32 v32, v32
	v_med3_f32 v29, v70, s16, v20
	v_med3_f32 v33, v71, s16, v20
	v_cvt_i32_f32_e32 v30, v30
	v_cvt_i32_f32_e32 v16, v16
	v_cvt_i32_f32_sdwa v28, v28 dst_sel:WORD_1 dst_unused:UNUSED_PAD src0_sel:DWORD
	v_cvt_i32_f32_sdwa v32, v32 dst_sel:WORD_1 dst_unused:UNUSED_PAD src0_sel:DWORD
	v_rndne_f32_e32 v29, v29
	v_rndne_f32_e32 v33, v33
	v_cvt_i32_f32_sdwa v29, v29 dst_sel:BYTE_3 dst_unused:UNUSED_PAD src0_sel:DWORD
	v_cvt_i32_f32_sdwa v33, v33 dst_sel:BYTE_3 dst_unused:UNUSED_PAD src0_sel:DWORD
	v_lshlrev_b32_e32 v31, 8, v31
	v_lshlrev_b32_e32 v17, 8, v17
	v_and_b32_e32 v31, 0xff00, v31
	v_and_b32_e32 v17, 0xff00, v17
	v_or_b32_sdwa v30, v31, v30 dst_sel:DWORD dst_unused:UNUSED_PAD src0_sel:DWORD src1_sel:BYTE_0
	v_or_b32_sdwa v16, v17, v16 dst_sel:DWORD dst_unused:UNUSED_PAD src0_sel:DWORD src1_sel:BYTE_0
	v_and_b32_e32 v17, 0xff0000, v32
	v_and_b32_e32 v28, 0xff0000, v28
	v_or_b32_e32 v17, v30, v17
	v_or_b32_e32 v16, v16, v28
	v_pk_mul_f32 v[4:5], v[92:93], v[78:79]
	v_or_b32_e32 v17, v17, v33
	v_or_b32_e32 v16, v16, v29
	ds_write2_b32 v25, v16, v17 offset1:1
	v_med3_f32 v17, v74, s16, v20
	v_med3_f32 v31, v75, s16, v20
	v_med3_f32 v4, v4, s16, v20
	v_med3_f32 v5, v5, s16, v20
	v_pk_mul_f32 v[72:73], v[90:91], v[72:73]
	v_pk_mul_f32 v[6:7], v[92:93], v[82:83]
	v_rndne_f32_e32 v17, v17
	v_rndne_f32_e32 v31, v31
	v_rndne_f32_e32 v4, v4
	v_rndne_f32_e32 v5, v5
	v_med3_f32 v16, v72, s16, v20
	v_med3_f32 v28, v76, s16, v20
	v_med3_f32 v30, v73, s16, v20
	v_med3_f32 v32, v77, s16, v20
	v_cvt_i32_f32_e32 v17, v17
	v_cvt_i32_f32_e32 v31, v31
	v_med3_f32 v2, v2, s16, v20
	v_med3_f32 v6, v6, s16, v20
	v_med3_f32 v3, v3, s16, v20
	v_med3_f32 v7, v7, s16, v20
	v_cvt_i32_f32_e32 v4, v4
	v_cvt_i32_f32_e32 v5, v5
	s_waitcnt vmcnt(0)
	v_pk_mul_f32 v[14:15], v[92:93], v[88:89]
	v_pk_mul_f32 v[78:79], v[90:91], v[86:87]
	v_rndne_f32_e32 v16, v16
	v_rndne_f32_e32 v28, v28
	v_rndne_f32_e32 v30, v30
	v_rndne_f32_e32 v32, v32
	v_rndne_f32_e32 v2, v2
	v_rndne_f32_e32 v6, v6
	v_rndne_f32_e32 v3, v3
	v_rndne_f32_e32 v7, v7
	v_med3_f32 v29, v78, s16, v20
	v_med3_f32 v33, v79, s16, v20
	v_cvt_i32_f32_e32 v30, v30
	v_cvt_i32_f32_e32 v16, v16
	v_cvt_i32_f32_sdwa v28, v28 dst_sel:WORD_1 dst_unused:UNUSED_PAD src0_sel:DWORD
	v_cvt_i32_f32_sdwa v32, v32 dst_sel:WORD_1 dst_unused:UNUSED_PAD src0_sel:DWORD
	v_med3_f32 v14, v14, s16, v20
	v_med3_f32 v15, v15, s16, v20
	v_cvt_i32_f32_e32 v3, v3
	v_cvt_i32_f32_e32 v2, v2
	v_cvt_i32_f32_sdwa v6, v6 dst_sel:WORD_1 dst_unused:UNUSED_PAD src0_sel:DWORD
	v_cvt_i32_f32_sdwa v7, v7 dst_sel:WORD_1 dst_unused:UNUSED_PAD src0_sel:DWORD
	v_rndne_f32_e32 v29, v29
	v_rndne_f32_e32 v33, v33
	v_rndne_f32_e32 v14, v14
	v_rndne_f32_e32 v15, v15
	v_cvt_i32_f32_sdwa v29, v29 dst_sel:BYTE_3 dst_unused:UNUSED_PAD src0_sel:DWORD
	v_cvt_i32_f32_sdwa v33, v33 dst_sel:BYTE_3 dst_unused:UNUSED_PAD src0_sel:DWORD
	v_lshlrev_b32_e32 v31, 8, v31
	v_lshlrev_b32_e32 v17, 8, v17
	v_cvt_i32_f32_sdwa v14, v14 dst_sel:BYTE_3 dst_unused:UNUSED_PAD src0_sel:DWORD
	v_cvt_i32_f32_sdwa v15, v15 dst_sel:BYTE_3 dst_unused:UNUSED_PAD src0_sel:DWORD
	v_lshlrev_b32_e32 v5, 8, v5
	v_lshlrev_b32_e32 v4, 8, v4
	v_and_b32_e32 v31, 0xff00, v31
	v_and_b32_e32 v17, 0xff00, v17
	v_and_b32_e32 v5, 0xff00, v5
	v_and_b32_e32 v4, 0xff00, v4
	v_or_b32_sdwa v30, v31, v30 dst_sel:DWORD dst_unused:UNUSED_PAD src0_sel:DWORD src1_sel:BYTE_0
	v_or_b32_sdwa v16, v17, v16 dst_sel:DWORD dst_unused:UNUSED_PAD src0_sel:DWORD src1_sel:BYTE_0
	v_and_b32_e32 v17, 0xff0000, v32
	v_and_b32_e32 v28, 0xff0000, v28
	v_or_b32_sdwa v3, v5, v3 dst_sel:DWORD dst_unused:UNUSED_PAD src0_sel:DWORD src1_sel:BYTE_0
	v_or_b32_sdwa v2, v4, v2 dst_sel:DWORD dst_unused:UNUSED_PAD src0_sel:DWORD src1_sel:BYTE_0
	v_and_b32_e32 v4, 0xff0000, v7
	v_and_b32_e32 v5, 0xff0000, v6
	v_or_b32_e32 v17, v30, v17
	v_or_b32_e32 v16, v16, v28
	v_or_b32_e32 v3, v3, v4
	v_or_b32_e32 v2, v2, v5
	v_or_b32_e32 v17, v17, v33
	v_or_b32_e32 v16, v16, v29
	v_or_b32_e32 v3, v3, v15
	v_or_b32_e32 v2, v2, v14
	ds_write2_b32 v26, v16, v17 offset1:1
	ds_write2_b32 v27, v2, v3 offset1:1
	v_add_u32_e32 v16, s8, v85
	v_and_b32_e32 v3, 24, v1
	s_waitcnt lgkmcnt(0)
	v_and_b32_e32 v2, 0xffffffc3, v16
	v_add_u32_e32 v28, s5, v3
	v_add3_u32 v6, v2, s17, v28
	v_cmp_lt_i32_e32 vcc, -1, v6
	v_lshl_add_u32 v29, v6, 2, v19
	v_mov_b32_e32 v2, 0
	v_mov_b32_e32 v3, 0
	v_mov_b32_e32 v4, 0
	v_mov_b32_e32 v5, 0
	s_and_saveexec_b64 s[8:9], vcc
	s_cbranch_execz .LBB0_972
	ds_read2_b32 v[2:3], v29 offset1:65
	ds_read2_b32 v[4:5], v29 offset0:130 offset1:195
